# conv LayerNorm z-gate loads issued once after the conv FMAs (into dead weight registers) instead of one step ahead with immediate waits
# speedup vs baseline: 1.0021x; 1.0021x over previous
; DI void conv_item(LAS unsigned char* lds, int item, const bf16_t* P, const float* cw, const float* cb, const float* lng, const float* lnb, bf16_t* MIX) {
;     ...
;     const int c = tid & 127, tq = tid >> 7;
;     float y[32];
;     {
;         float w[31];
; #pragma unroll
;         for (int k = 0; k < 31; ++k) w[k] = cw[k * 1024 + cbase + c];
;         const float bias = cb[cbase + c];
; #pragma unroll
;         for (int i = 0; i < 32; ++i) y[i] = bias;
;         float uw[62];
; #pragma unroll
;         for (int j = 0; j < 62; ++j) uw[j] = U[(tq * 32 + j) * 128 + c];
; #pragma unroll
;         for (int i = 0; i < 32; ++i)
; #pragma unroll
;             for (int k = 0; k < 31; ++k) y[i] += w[k] * uw[i + k];
.LBB0_517:
	s_or_b64 exec, exec, s[26:27]
	s_lshl_b32 s12, s37, 2
	v_lshrrev_b32_e32 v251, 6, v253
	v_lshlrev_b32_e32 v251, 13, v251
	v_lshl_add_u32 v251, v252, 3, v251
	s_waitcnt lgkmcnt(0)
	s_barrier
	ds_read_b64 v[222:223], v251
	ds_read_b64 v[224:225], v251 offset:512
	ds_read_b64 v[226:227], v251 offset:1024
	ds_read_b64 v[228:229], v251 offset:1536
	ds_read_b64 v[230:231], v251 offset:2048
	ds_read_b64 v[232:233], v251 offset:2560
	ds_read_b64 v[234:235], v251 offset:3072
	ds_read_b64 v[236:237], v251 offset:3584
	ds_read_b64 v[238:239], v251 offset:4096
	ds_read_b64 v[240:241], v251 offset:4608
	ds_read_b64 v[242:243], v251 offset:5120
	ds_read_b64 v[244:245], v251 offset:5632
	ds_read_b64 v[246:247], v251 offset:6144
	ds_read_b64 v[248:249], v251 offset:6656
	ds_read_b64 v[8:9], v251 offset:7168
	ds_read_b64 v[10:11], v251 offset:7680
	ds_read_b64 v[12:13], v251 offset:8192
	ds_read_b64 v[14:15], v251 offset:8704
	ds_read_b64 v[16:17], v251 offset:9216
	ds_read_b64 v[18:19], v251 offset:9728
	ds_read_b64 v[20:21], v251 offset:10240
	ds_read_b64 v[22:23], v251 offset:10752
	ds_read_b64 v[28:29], v251 offset:11264
	ds_read_b64 v[30:31], v251 offset:11776
	ds_read_b64 v[32:33], v251 offset:12288
	ds_read_b64 v[34:35], v251 offset:12800
	ds_read_b64 v[36:37], v251 offset:13312
	ds_read_b64 v[38:39], v251 offset:13824
	ds_read_b64 v[50:51], v251 offset:14336
	ds_read_b64 v[52:53], v251 offset:14848
	ds_read_b64 v[54:55], v251 offset:15360
	ds_read_b64 v[56:57], v251 offset:15872
	ds_read_b64 v[58:59], v251 offset:16384
	ds_read_b64 v[60:61], v251 offset:16896
	ds_read_b64 v[62:63], v251 offset:17408
	ds_read_b64 v[64:65], v251 offset:17920
	ds_read_b64 v[66:67], v251 offset:18432
	ds_read_b64 v[92:93], v251 offset:18944
	ds_read_b64 v[94:95], v251 offset:19456
	ds_read_b64 v[96:97], v251 offset:19968
	ds_read_b64 v[98:99], v251 offset:20480
	ds_read_b64 v[100:101], v251 offset:20992
	ds_read_b64 v[102:103], v251 offset:21504
	ds_read_b64 v[104:105], v251 offset:22016
	ds_read_b64 v[106:107], v251 offset:22528
	ds_read_b64 v[108:109], v251 offset:23040
	s_waitcnt vmcnt(0) lgkmcnt(0)
	s_barrier
	v_pk_fma_f32 v[190:191], v[126:127], v[222:223], v[188:189]
	v_pk_fma_f32 v[190:191], v[128:129], v[224:225], v[190:191]
	v_pk_fma_f32 v[192:193], v[126:127], v[224:225], v[188:189]
	v_pk_fma_f32 v[190:191], v[130:131], v[226:227], v[190:191]
	v_pk_fma_f32 v[192:193], v[128:129], v[226:227], v[192:193]
	v_pk_fma_f32 v[194:195], v[126:127], v[226:227], v[188:189]
	v_pk_fma_f32 v[190:191], v[132:133], v[228:229], v[190:191]
	v_pk_fma_f32 v[192:193], v[130:131], v[228:229], v[192:193]
	v_pk_fma_f32 v[194:195], v[128:129], v[228:229], v[194:195]
	v_pk_fma_f32 v[196:197], v[126:127], v[228:229], v[188:189]
	v_pk_fma_f32 v[190:191], v[134:135], v[230:231], v[190:191]
	v_pk_fma_f32 v[192:193], v[132:133], v[230:231], v[192:193]
	v_pk_fma_f32 v[194:195], v[130:131], v[230:231], v[194:195]
	v_pk_fma_f32 v[196:197], v[128:129], v[230:231], v[196:197]
	v_pk_fma_f32 v[198:199], v[126:127], v[230:231], v[188:189]
	v_pk_fma_f32 v[190:191], v[136:137], v[232:233], v[190:191]
	v_pk_fma_f32 v[192:193], v[134:135], v[232:233], v[192:193]
	v_pk_fma_f32 v[194:195], v[132:133], v[232:233], v[194:195]
	v_pk_fma_f32 v[196:197], v[130:131], v[232:233], v[196:197]
	v_pk_fma_f32 v[198:199], v[128:129], v[232:233], v[198:199]
	v_pk_fma_f32 v[200:201], v[126:127], v[232:233], v[188:189]
	v_pk_fma_f32 v[190:191], v[138:139], v[234:235], v[190:191]
	v_pk_fma_f32 v[192:193], v[136:137], v[234:235], v[192:193]
	v_pk_fma_f32 v[194:195], v[134:135], v[234:235], v[194:195]
	v_pk_fma_f32 v[196:197], v[132:133], v[234:235], v[196:197]
	v_pk_fma_f32 v[198:199], v[130:131], v[234:235], v[198:199]
	v_pk_fma_f32 v[200:201], v[128:129], v[234:235], v[200:201]
	v_pk_fma_f32 v[202:203], v[126:127], v[234:235], v[188:189]
	v_pk_fma_f32 v[190:191], v[140:141], v[236:237], v[190:191]
	v_pk_fma_f32 v[192:193], v[138:139], v[236:237], v[192:193]
	v_pk_fma_f32 v[194:195], v[136:137], v[236:237], v[194:195]
	v_pk_fma_f32 v[196:197], v[134:135], v[236:237], v[196:197]
	v_pk_fma_f32 v[198:199], v[132:133], v[236:237], v[198:199]
	v_pk_fma_f32 v[200:201], v[130:131], v[236:237], v[200:201]
	v_pk_fma_f32 v[202:203], v[128:129], v[236:237], v[202:203]
	v_pk_fma_f32 v[204:205], v[126:127], v[236:237], v[188:189]
	v_pk_fma_f32 v[190:191], v[142:143], v[238:239], v[190:191]
	v_pk_fma_f32 v[192:193], v[140:141], v[238:239], v[192:193]
	v_pk_fma_f32 v[194:195], v[138:139], v[238:239], v[194:195]
	v_pk_fma_f32 v[196:197], v[136:137], v[238:239], v[196:197]
	v_pk_fma_f32 v[198:199], v[134:135], v[238:239], v[198:199]
	v_pk_fma_f32 v[200:201], v[132:133], v[238:239], v[200:201]
	v_pk_fma_f32 v[202:203], v[130:131], v[238:239], v[202:203]
	v_pk_fma_f32 v[204:205], v[128:129], v[238:239], v[204:205]
	v_pk_fma_f32 v[206:207], v[126:127], v[238:239], v[188:189]
	v_pk_fma_f32 v[190:191], v[144:145], v[240:241], v[190:191]
	v_pk_fma_f32 v[192:193], v[142:143], v[240:241], v[192:193]
	v_pk_fma_f32 v[194:195], v[140:141], v[240:241], v[194:195]
	v_pk_fma_f32 v[196:197], v[138:139], v[240:241], v[196:197]
	v_pk_fma_f32 v[198:199], v[136:137], v[240:241], v[198:199]
	v_pk_fma_f32 v[200:201], v[134:135], v[240:241], v[200:201]
	v_pk_fma_f32 v[202:203], v[132:133], v[240:241], v[202:203]
	v_pk_fma_f32 v[204:205], v[130:131], v[240:241], v[204:205]
	v_pk_fma_f32 v[206:207], v[128:129], v[240:241], v[206:207]
	v_pk_fma_f32 v[208:209], v[126:127], v[240:241], v[188:189]
	v_pk_fma_f32 v[190:191], v[146:147], v[242:243], v[190:191]
	v_pk_fma_f32 v[192:193], v[144:145], v[242:243], v[192:193]
; DI void conv_item(LAS unsigned char* lds, int item, const bf16_t* P, const float* cw, const float* cb, const float* lng, const float* lnb, bf16_t* MIX) {
;     ...
;         for (int i = 0; i < 32; ++i)
; #pragma unroll
;             for (int k = 0; k < 31; ++k) y[i] += w[k] * uw[i + k];
	v_pk_fma_f32 v[194:195], v[142:143], v[242:243], v[194:195]
	v_pk_fma_f32 v[196:197], v[140:141], v[242:243], v[196:197]
	v_pk_fma_f32 v[198:199], v[138:139], v[242:243], v[198:199]
	v_pk_fma_f32 v[200:201], v[136:137], v[242:243], v[200:201]
	v_pk_fma_f32 v[202:203], v[134:135], v[242:243], v[202:203]
	v_pk_fma_f32 v[204:205], v[132:133], v[242:243], v[204:205]
	v_pk_fma_f32 v[206:207], v[130:131], v[242:243], v[206:207]
	v_pk_fma_f32 v[208:209], v[128:129], v[242:243], v[208:209]
	v_pk_fma_f32 v[210:211], v[126:127], v[242:243], v[188:189]
	v_pk_fma_f32 v[190:191], v[148:149], v[244:245], v[190:191]
	v_pk_fma_f32 v[192:193], v[146:147], v[244:245], v[192:193]
	v_pk_fma_f32 v[194:195], v[144:145], v[244:245], v[194:195]
	v_pk_fma_f32 v[196:197], v[142:143], v[244:245], v[196:197]
	v_pk_fma_f32 v[198:199], v[140:141], v[244:245], v[198:199]
	v_pk_fma_f32 v[200:201], v[138:139], v[244:245], v[200:201]
	v_pk_fma_f32 v[202:203], v[136:137], v[244:245], v[202:203]
	v_pk_fma_f32 v[204:205], v[134:135], v[244:245], v[204:205]
	v_pk_fma_f32 v[206:207], v[132:133], v[244:245], v[206:207]
	v_pk_fma_f32 v[208:209], v[130:131], v[244:245], v[208:209]
	v_pk_fma_f32 v[210:211], v[128:129], v[244:245], v[210:211]
	v_pk_fma_f32 v[212:213], v[126:127], v[244:245], v[188:189]
	v_pk_fma_f32 v[190:191], v[150:151], v[246:247], v[190:191]
	v_pk_fma_f32 v[192:193], v[148:149], v[246:247], v[192:193]
	v_pk_fma_f32 v[194:195], v[146:147], v[246:247], v[194:195]
	v_pk_fma_f32 v[196:197], v[144:145], v[246:247], v[196:197]
	v_pk_fma_f32 v[198:199], v[142:143], v[246:247], v[198:199]
	v_pk_fma_f32 v[200:201], v[140:141], v[246:247], v[200:201]
	v_pk_fma_f32 v[202:203], v[138:139], v[246:247], v[202:203]
	v_pk_fma_f32 v[204:205], v[136:137], v[246:247], v[204:205]
	v_pk_fma_f32 v[206:207], v[134:135], v[246:247], v[206:207]
	v_pk_fma_f32 v[208:209], v[132:133], v[246:247], v[208:209]
	v_pk_fma_f32 v[210:211], v[130:131], v[246:247], v[210:211]
	v_pk_fma_f32 v[212:213], v[128:129], v[246:247], v[212:213]
	v_pk_fma_f32 v[214:215], v[126:127], v[246:247], v[188:189]
	v_pk_fma_f32 v[190:191], v[152:153], v[248:249], v[190:191]
	v_pk_fma_f32 v[192:193], v[150:151], v[248:249], v[192:193]
	v_pk_fma_f32 v[194:195], v[148:149], v[248:249], v[194:195]
	v_pk_fma_f32 v[196:197], v[146:147], v[248:249], v[196:197]
	v_pk_fma_f32 v[198:199], v[144:145], v[248:249], v[198:199]
	v_pk_fma_f32 v[200:201], v[142:143], v[248:249], v[200:201]
	v_pk_fma_f32 v[202:203], v[140:141], v[248:249], v[202:203]
	v_pk_fma_f32 v[204:205], v[138:139], v[248:249], v[204:205]
	v_pk_fma_f32 v[206:207], v[136:137], v[248:249], v[206:207]
	v_pk_fma_f32 v[208:209], v[134:135], v[248:249], v[208:209]
	v_pk_fma_f32 v[210:211], v[132:133], v[248:249], v[210:211]
	v_pk_fma_f32 v[212:213], v[130:131], v[248:249], v[212:213]
	v_pk_fma_f32 v[214:215], v[128:129], v[248:249], v[214:215]
	v_pk_fma_f32 v[216:217], v[126:127], v[248:249], v[188:189]
	v_pk_fma_f32 v[190:191], v[154:155], v[8:9], v[190:191]
	v_pk_fma_f32 v[192:193], v[152:153], v[8:9], v[192:193]
	v_pk_fma_f32 v[194:195], v[150:151], v[8:9], v[194:195]
	v_pk_fma_f32 v[196:197], v[148:149], v[8:9], v[196:197]
	v_pk_fma_f32 v[198:199], v[146:147], v[8:9], v[198:199]
	v_pk_fma_f32 v[200:201], v[144:145], v[8:9], v[200:201]
	v_pk_fma_f32 v[202:203], v[142:143], v[8:9], v[202:203]
	v_pk_fma_f32 v[204:205], v[140:141], v[8:9], v[204:205]
	v_pk_fma_f32 v[206:207], v[138:139], v[8:9], v[206:207]
	v_pk_fma_f32 v[208:209], v[136:137], v[8:9], v[208:209]
	v_pk_fma_f32 v[210:211], v[134:135], v[8:9], v[210:211]
	v_pk_fma_f32 v[212:213], v[132:133], v[8:9], v[212:213]
	v_pk_fma_f32 v[214:215], v[130:131], v[8:9], v[214:215]
	v_pk_fma_f32 v[216:217], v[128:129], v[8:9], v[216:217]
	v_pk_fma_f32 v[218:219], v[126:127], v[8:9], v[188:189]
	v_pk_fma_f32 v[190:191], v[156:157], v[10:11], v[190:191]
	v_pk_fma_f32 v[192:193], v[154:155], v[10:11], v[192:193]
	v_pk_fma_f32 v[194:195], v[152:153], v[10:11], v[194:195]
	v_pk_fma_f32 v[196:197], v[150:151], v[10:11], v[196:197]
	v_pk_fma_f32 v[198:199], v[148:149], v[10:11], v[198:199]
	v_pk_fma_f32 v[200:201], v[146:147], v[10:11], v[200:201]
	v_pk_fma_f32 v[202:203], v[144:145], v[10:11], v[202:203]
	v_pk_fma_f32 v[204:205], v[142:143], v[10:11], v[204:205]
	v_pk_fma_f32 v[206:207], v[140:141], v[10:11], v[206:207]
	v_pk_fma_f32 v[208:209], v[138:139], v[10:11], v[208:209]
	v_pk_fma_f32 v[210:211], v[136:137], v[10:11], v[210:211]
	v_pk_fma_f32 v[212:213], v[134:135], v[10:11], v[212:213]
	v_pk_fma_f32 v[214:215], v[132:133], v[10:11], v[214:215]
	v_pk_fma_f32 v[216:217], v[130:131], v[10:11], v[216:217]
	v_pk_fma_f32 v[218:219], v[128:129], v[10:11], v[218:219]
	v_pk_fma_f32 v[220:221], v[126:127], v[10:11], v[188:189]
	v_pk_fma_f32 v[190:191], v[158:159], v[12:13], v[190:191]
	v_pk_fma_f32 v[192:193], v[156:157], v[12:13], v[192:193]
	v_pk_fma_f32 v[194:195], v[154:155], v[12:13], v[194:195]
	v_pk_fma_f32 v[196:197], v[152:153], v[12:13], v[196:197]
	v_pk_fma_f32 v[198:199], v[150:151], v[12:13], v[198:199]
	v_pk_fma_f32 v[200:201], v[148:149], v[12:13], v[200:201]
	v_pk_fma_f32 v[202:203], v[146:147], v[12:13], v[202:203]
	v_pk_fma_f32 v[204:205], v[144:145], v[12:13], v[204:205]
	v_pk_fma_f32 v[206:207], v[142:143], v[12:13], v[206:207]
	v_pk_fma_f32 v[208:209], v[140:141], v[12:13], v[208:209]
	v_pk_fma_f32 v[210:211], v[138:139], v[12:13], v[210:211]
	v_pk_fma_f32 v[212:213], v[136:137], v[12:13], v[212:213]
	v_pk_fma_f32 v[214:215], v[134:135], v[12:13], v[214:215]
	v_pk_fma_f32 v[216:217], v[132:133], v[12:13], v[216:217]
	v_pk_fma_f32 v[218:219], v[130:131], v[12:13], v[218:219]
; DI void conv_item(LAS unsigned char* lds, int item, const bf16_t* P, const float* cw, const float* cb, const float* lng, const float* lnb, bf16_t* MIX) {
;     ...
;         for (int i = 0; i < 32; ++i)
; #pragma unroll
;             for (int k = 0; k < 31; ++k) y[i] += w[k] * uw[i + k];
	v_pk_fma_f32 v[220:221], v[128:129], v[12:13], v[220:221]
	v_pk_fma_f32 v[190:191], v[160:161], v[14:15], v[190:191]
	v_pk_fma_f32 v[192:193], v[158:159], v[14:15], v[192:193]
	v_pk_fma_f32 v[194:195], v[156:157], v[14:15], v[194:195]
	v_pk_fma_f32 v[196:197], v[154:155], v[14:15], v[196:197]
	v_pk_fma_f32 v[198:199], v[152:153], v[14:15], v[198:199]
	v_pk_fma_f32 v[200:201], v[150:151], v[14:15], v[200:201]
	v_pk_fma_f32 v[202:203], v[148:149], v[14:15], v[202:203]
	v_pk_fma_f32 v[204:205], v[146:147], v[14:15], v[204:205]
	v_pk_fma_f32 v[206:207], v[144:145], v[14:15], v[206:207]
	v_pk_fma_f32 v[208:209], v[142:143], v[14:15], v[208:209]
	v_pk_fma_f32 v[210:211], v[140:141], v[14:15], v[210:211]
	v_pk_fma_f32 v[212:213], v[138:139], v[14:15], v[212:213]
	v_pk_fma_f32 v[214:215], v[136:137], v[14:15], v[214:215]
	v_pk_fma_f32 v[216:217], v[134:135], v[14:15], v[216:217]
	v_pk_fma_f32 v[218:219], v[132:133], v[14:15], v[218:219]
	v_pk_fma_f32 v[220:221], v[130:131], v[14:15], v[220:221]
	v_pk_fma_f32 v[190:191], v[162:163], v[16:17], v[190:191]
	v_pk_fma_f32 v[192:193], v[160:161], v[16:17], v[192:193]
	v_pk_fma_f32 v[194:195], v[158:159], v[16:17], v[194:195]
	v_pk_fma_f32 v[196:197], v[156:157], v[16:17], v[196:197]
	v_pk_fma_f32 v[198:199], v[154:155], v[16:17], v[198:199]
	v_pk_fma_f32 v[200:201], v[152:153], v[16:17], v[200:201]
	v_pk_fma_f32 v[202:203], v[150:151], v[16:17], v[202:203]
	v_pk_fma_f32 v[204:205], v[148:149], v[16:17], v[204:205]
	v_pk_fma_f32 v[206:207], v[146:147], v[16:17], v[206:207]
	v_pk_fma_f32 v[208:209], v[144:145], v[16:17], v[208:209]
	v_pk_fma_f32 v[210:211], v[142:143], v[16:17], v[210:211]
	v_pk_fma_f32 v[212:213], v[140:141], v[16:17], v[212:213]
	v_pk_fma_f32 v[214:215], v[138:139], v[16:17], v[214:215]
	v_pk_fma_f32 v[216:217], v[136:137], v[16:17], v[216:217]
	v_pk_fma_f32 v[218:219], v[134:135], v[16:17], v[218:219]
	v_pk_fma_f32 v[220:221], v[132:133], v[16:17], v[220:221]
	v_pk_fma_f32 v[190:191], v[164:165], v[18:19], v[190:191]
	v_pk_fma_f32 v[192:193], v[162:163], v[18:19], v[192:193]
	v_pk_fma_f32 v[194:195], v[160:161], v[18:19], v[194:195]
	v_pk_fma_f32 v[196:197], v[158:159], v[18:19], v[196:197]
	v_pk_fma_f32 v[198:199], v[156:157], v[18:19], v[198:199]
	v_pk_fma_f32 v[200:201], v[154:155], v[18:19], v[200:201]
	v_pk_fma_f32 v[202:203], v[152:153], v[18:19], v[202:203]
	v_pk_fma_f32 v[204:205], v[150:151], v[18:19], v[204:205]
	v_pk_fma_f32 v[206:207], v[148:149], v[18:19], v[206:207]
	v_pk_fma_f32 v[208:209], v[146:147], v[18:19], v[208:209]
	v_pk_fma_f32 v[210:211], v[144:145], v[18:19], v[210:211]
	v_pk_fma_f32 v[212:213], v[142:143], v[18:19], v[212:213]
	v_pk_fma_f32 v[214:215], v[140:141], v[18:19], v[214:215]
	v_pk_fma_f32 v[216:217], v[138:139], v[18:19], v[216:217]
	v_pk_fma_f32 v[218:219], v[136:137], v[18:19], v[218:219]
	v_pk_fma_f32 v[220:221], v[134:135], v[18:19], v[220:221]
	v_pk_fma_f32 v[190:191], v[166:167], v[20:21], v[190:191]
	v_pk_fma_f32 v[192:193], v[164:165], v[20:21], v[192:193]
	v_pk_fma_f32 v[194:195], v[162:163], v[20:21], v[194:195]
	v_pk_fma_f32 v[196:197], v[160:161], v[20:21], v[196:197]
	v_pk_fma_f32 v[198:199], v[158:159], v[20:21], v[198:199]
	v_pk_fma_f32 v[200:201], v[156:157], v[20:21], v[200:201]
	v_pk_fma_f32 v[202:203], v[154:155], v[20:21], v[202:203]
	v_pk_fma_f32 v[204:205], v[152:153], v[20:21], v[204:205]
	v_pk_fma_f32 v[206:207], v[150:151], v[20:21], v[206:207]
	v_pk_fma_f32 v[208:209], v[148:149], v[20:21], v[208:209]
	v_pk_fma_f32 v[210:211], v[146:147], v[20:21], v[210:211]
	v_pk_fma_f32 v[212:213], v[144:145], v[20:21], v[212:213]
	v_pk_fma_f32 v[214:215], v[142:143], v[20:21], v[214:215]
	v_pk_fma_f32 v[216:217], v[140:141], v[20:21], v[216:217]
	v_pk_fma_f32 v[218:219], v[138:139], v[20:21], v[218:219]
	v_pk_fma_f32 v[220:221], v[136:137], v[20:21], v[220:221]
	v_pk_fma_f32 v[190:191], v[168:169], v[22:23], v[190:191]
	v_pk_fma_f32 v[192:193], v[166:167], v[22:23], v[192:193]
	v_pk_fma_f32 v[194:195], v[164:165], v[22:23], v[194:195]
	v_pk_fma_f32 v[196:197], v[162:163], v[22:23], v[196:197]
	v_pk_fma_f32 v[198:199], v[160:161], v[22:23], v[198:199]
	v_pk_fma_f32 v[200:201], v[158:159], v[22:23], v[200:201]
	v_pk_fma_f32 v[202:203], v[156:157], v[22:23], v[202:203]
	v_pk_fma_f32 v[204:205], v[154:155], v[22:23], v[204:205]
	v_pk_fma_f32 v[206:207], v[152:153], v[22:23], v[206:207]
	v_pk_fma_f32 v[208:209], v[150:151], v[22:23], v[208:209]
	v_pk_fma_f32 v[210:211], v[148:149], v[22:23], v[210:211]
	v_pk_fma_f32 v[212:213], v[146:147], v[22:23], v[212:213]
	v_pk_fma_f32 v[214:215], v[144:145], v[22:23], v[214:215]
	v_pk_fma_f32 v[216:217], v[142:143], v[22:23], v[216:217]
	v_pk_fma_f32 v[218:219], v[140:141], v[22:23], v[218:219]
	v_pk_fma_f32 v[220:221], v[138:139], v[22:23], v[220:221]
	v_pk_fma_f32 v[190:191], v[170:171], v[28:29], v[190:191]
	v_pk_fma_f32 v[192:193], v[168:169], v[28:29], v[192:193]
	v_pk_fma_f32 v[194:195], v[166:167], v[28:29], v[194:195]
	v_pk_fma_f32 v[196:197], v[164:165], v[28:29], v[196:197]
	v_pk_fma_f32 v[198:199], v[162:163], v[28:29], v[198:199]
	v_pk_fma_f32 v[200:201], v[160:161], v[28:29], v[200:201]
	v_pk_fma_f32 v[202:203], v[158:159], v[28:29], v[202:203]
	v_pk_fma_f32 v[204:205], v[156:157], v[28:29], v[204:205]
	v_pk_fma_f32 v[206:207], v[154:155], v[28:29], v[206:207]
	v_pk_fma_f32 v[208:209], v[152:153], v[28:29], v[208:209]
	v_pk_fma_f32 v[210:211], v[150:151], v[28:29], v[210:211]
	v_pk_fma_f32 v[212:213], v[148:149], v[28:29], v[212:213]
	v_pk_fma_f32 v[214:215], v[146:147], v[28:29], v[214:215]
	v_pk_fma_f32 v[216:217], v[144:145], v[28:29], v[216:217]
	v_pk_fma_f32 v[218:219], v[142:143], v[28:29], v[218:219]
; DI void conv_item(LAS unsigned char* lds, int item, const bf16_t* P, const float* cw, const float* cb, const float* lng, const float* lnb, bf16_t* MIX) {
;     ...
;         for (int i = 0; i < 32; ++i)
; #pragma unroll
;             for (int k = 0; k < 31; ++k) y[i] += w[k] * uw[i + k];
	v_pk_fma_f32 v[220:221], v[140:141], v[28:29], v[220:221]
	v_pk_fma_f32 v[190:191], v[172:173], v[30:31], v[190:191]
	v_pk_fma_f32 v[192:193], v[170:171], v[30:31], v[192:193]
	v_pk_fma_f32 v[194:195], v[168:169], v[30:31], v[194:195]
	v_pk_fma_f32 v[196:197], v[166:167], v[30:31], v[196:197]
	v_pk_fma_f32 v[198:199], v[164:165], v[30:31], v[198:199]
	v_pk_fma_f32 v[200:201], v[162:163], v[30:31], v[200:201]
	v_pk_fma_f32 v[202:203], v[160:161], v[30:31], v[202:203]
	v_pk_fma_f32 v[204:205], v[158:159], v[30:31], v[204:205]
	v_pk_fma_f32 v[206:207], v[156:157], v[30:31], v[206:207]
	v_pk_fma_f32 v[208:209], v[154:155], v[30:31], v[208:209]
	v_pk_fma_f32 v[210:211], v[152:153], v[30:31], v[210:211]
	v_pk_fma_f32 v[212:213], v[150:151], v[30:31], v[212:213]
	v_pk_fma_f32 v[214:215], v[148:149], v[30:31], v[214:215]
	v_pk_fma_f32 v[216:217], v[146:147], v[30:31], v[216:217]
	v_pk_fma_f32 v[218:219], v[144:145], v[30:31], v[218:219]
	v_pk_fma_f32 v[220:221], v[142:143], v[30:31], v[220:221]
	v_pk_fma_f32 v[190:191], v[174:175], v[32:33], v[190:191]
	v_pk_fma_f32 v[192:193], v[172:173], v[32:33], v[192:193]
	v_pk_fma_f32 v[194:195], v[170:171], v[32:33], v[194:195]
	v_pk_fma_f32 v[196:197], v[168:169], v[32:33], v[196:197]
	v_pk_fma_f32 v[198:199], v[166:167], v[32:33], v[198:199]
	v_pk_fma_f32 v[200:201], v[164:165], v[32:33], v[200:201]
	v_pk_fma_f32 v[202:203], v[162:163], v[32:33], v[202:203]
	v_pk_fma_f32 v[204:205], v[160:161], v[32:33], v[204:205]
	v_pk_fma_f32 v[206:207], v[158:159], v[32:33], v[206:207]
	v_pk_fma_f32 v[208:209], v[156:157], v[32:33], v[208:209]
	v_pk_fma_f32 v[210:211], v[154:155], v[32:33], v[210:211]
	v_pk_fma_f32 v[212:213], v[152:153], v[32:33], v[212:213]
	v_pk_fma_f32 v[214:215], v[150:151], v[32:33], v[214:215]
	v_pk_fma_f32 v[216:217], v[148:149], v[32:33], v[216:217]
	v_pk_fma_f32 v[218:219], v[146:147], v[32:33], v[218:219]
	v_pk_fma_f32 v[220:221], v[144:145], v[32:33], v[220:221]
	v_pk_fma_f32 v[190:191], v[176:177], v[34:35], v[190:191]
	v_pk_fma_f32 v[192:193], v[174:175], v[34:35], v[192:193]
	v_pk_fma_f32 v[194:195], v[172:173], v[34:35], v[194:195]
	v_pk_fma_f32 v[196:197], v[170:171], v[34:35], v[196:197]
	v_pk_fma_f32 v[198:199], v[168:169], v[34:35], v[198:199]
	v_pk_fma_f32 v[200:201], v[166:167], v[34:35], v[200:201]
	v_pk_fma_f32 v[202:203], v[164:165], v[34:35], v[202:203]
	v_pk_fma_f32 v[204:205], v[162:163], v[34:35], v[204:205]
	v_pk_fma_f32 v[206:207], v[160:161], v[34:35], v[206:207]
	v_pk_fma_f32 v[208:209], v[158:159], v[34:35], v[208:209]
	v_pk_fma_f32 v[210:211], v[156:157], v[34:35], v[210:211]
	v_pk_fma_f32 v[212:213], v[154:155], v[34:35], v[212:213]
	v_pk_fma_f32 v[214:215], v[152:153], v[34:35], v[214:215]
	v_pk_fma_f32 v[216:217], v[150:151], v[34:35], v[216:217]
	v_pk_fma_f32 v[218:219], v[148:149], v[34:35], v[218:219]
	v_pk_fma_f32 v[220:221], v[146:147], v[34:35], v[220:221]
	v_pk_fma_f32 v[190:191], v[178:179], v[36:37], v[190:191]
	v_pk_fma_f32 v[192:193], v[176:177], v[36:37], v[192:193]
	v_pk_fma_f32 v[194:195], v[174:175], v[36:37], v[194:195]
	v_pk_fma_f32 v[196:197], v[172:173], v[36:37], v[196:197]
	v_pk_fma_f32 v[198:199], v[170:171], v[36:37], v[198:199]
	v_pk_fma_f32 v[200:201], v[168:169], v[36:37], v[200:201]
	v_pk_fma_f32 v[202:203], v[166:167], v[36:37], v[202:203]
	v_pk_fma_f32 v[204:205], v[164:165], v[36:37], v[204:205]
	v_pk_fma_f32 v[206:207], v[162:163], v[36:37], v[206:207]
	v_pk_fma_f32 v[208:209], v[160:161], v[36:37], v[208:209]
	v_pk_fma_f32 v[210:211], v[158:159], v[36:37], v[210:211]
	v_pk_fma_f32 v[212:213], v[156:157], v[36:37], v[212:213]
	v_pk_fma_f32 v[214:215], v[154:155], v[36:37], v[214:215]
	v_pk_fma_f32 v[216:217], v[152:153], v[36:37], v[216:217]
	v_pk_fma_f32 v[218:219], v[150:151], v[36:37], v[218:219]
	v_pk_fma_f32 v[220:221], v[148:149], v[36:37], v[220:221]
	v_pk_fma_f32 v[190:191], v[180:181], v[38:39], v[190:191]
	v_pk_fma_f32 v[192:193], v[178:179], v[38:39], v[192:193]
	v_pk_fma_f32 v[194:195], v[176:177], v[38:39], v[194:195]
	v_pk_fma_f32 v[196:197], v[174:175], v[38:39], v[196:197]
	v_pk_fma_f32 v[198:199], v[172:173], v[38:39], v[198:199]
	v_pk_fma_f32 v[200:201], v[170:171], v[38:39], v[200:201]
	v_pk_fma_f32 v[202:203], v[168:169], v[38:39], v[202:203]
	v_pk_fma_f32 v[204:205], v[166:167], v[38:39], v[204:205]
	v_pk_fma_f32 v[206:207], v[164:165], v[38:39], v[206:207]
	v_pk_fma_f32 v[208:209], v[162:163], v[38:39], v[208:209]
	v_pk_fma_f32 v[210:211], v[160:161], v[38:39], v[210:211]
	v_pk_fma_f32 v[212:213], v[158:159], v[38:39], v[212:213]
	v_pk_fma_f32 v[214:215], v[156:157], v[38:39], v[214:215]
	v_pk_fma_f32 v[216:217], v[154:155], v[38:39], v[216:217]
	v_pk_fma_f32 v[218:219], v[152:153], v[38:39], v[218:219]
	v_pk_fma_f32 v[220:221], v[150:151], v[38:39], v[220:221]
	v_pk_fma_f32 v[190:191], v[182:183], v[50:51], v[190:191]
	v_pk_fma_f32 v[192:193], v[180:181], v[50:51], v[192:193]
	v_pk_fma_f32 v[194:195], v[178:179], v[50:51], v[194:195]
	v_pk_fma_f32 v[196:197], v[176:177], v[50:51], v[196:197]
	v_pk_fma_f32 v[198:199], v[174:175], v[50:51], v[198:199]
	v_pk_fma_f32 v[200:201], v[172:173], v[50:51], v[200:201]
	v_pk_fma_f32 v[202:203], v[170:171], v[50:51], v[202:203]
	v_pk_fma_f32 v[204:205], v[168:169], v[50:51], v[204:205]
	v_pk_fma_f32 v[206:207], v[166:167], v[50:51], v[206:207]
	v_pk_fma_f32 v[208:209], v[164:165], v[50:51], v[208:209]
	v_pk_fma_f32 v[210:211], v[162:163], v[50:51], v[210:211]
	v_pk_fma_f32 v[212:213], v[160:161], v[50:51], v[212:213]
	v_pk_fma_f32 v[214:215], v[158:159], v[50:51], v[214:215]
	v_pk_fma_f32 v[216:217], v[156:157], v[50:51], v[216:217]
	v_pk_fma_f32 v[218:219], v[154:155], v[50:51], v[218:219]
; DI void conv_item(LAS unsigned char* lds, int item, const bf16_t* P, const float* cw, const float* cb, const float* lng, const float* lnb, bf16_t* MIX) {
;     ...
;         for (int i = 0; i < 32; ++i)
; #pragma unroll
;             for (int k = 0; k < 31; ++k) y[i] += w[k] * uw[i + k];
	v_pk_fma_f32 v[220:221], v[152:153], v[50:51], v[220:221]
	v_pk_fma_f32 v[190:191], v[184:185], v[52:53], v[190:191]
	v_pk_fma_f32 v[192:193], v[182:183], v[52:53], v[192:193]
	v_pk_fma_f32 v[194:195], v[180:181], v[52:53], v[194:195]
	v_pk_fma_f32 v[196:197], v[178:179], v[52:53], v[196:197]
	v_pk_fma_f32 v[198:199], v[176:177], v[52:53], v[198:199]
	v_pk_fma_f32 v[200:201], v[174:175], v[52:53], v[200:201]
	v_pk_fma_f32 v[202:203], v[172:173], v[52:53], v[202:203]
	v_pk_fma_f32 v[204:205], v[170:171], v[52:53], v[204:205]
	v_pk_fma_f32 v[206:207], v[168:169], v[52:53], v[206:207]
	v_pk_fma_f32 v[208:209], v[166:167], v[52:53], v[208:209]
	v_pk_fma_f32 v[210:211], v[164:165], v[52:53], v[210:211]
	v_pk_fma_f32 v[212:213], v[162:163], v[52:53], v[212:213]
	v_pk_fma_f32 v[214:215], v[160:161], v[52:53], v[214:215]
	v_pk_fma_f32 v[216:217], v[158:159], v[52:53], v[216:217]
	v_pk_fma_f32 v[218:219], v[156:157], v[52:53], v[218:219]
	v_pk_fma_f32 v[220:221], v[154:155], v[52:53], v[220:221]
	v_pk_fma_f32 v[190:191], v[186:187], v[54:55], v[190:191]
	v_pk_fma_f32 v[192:193], v[184:185], v[54:55], v[192:193]
	v_pk_fma_f32 v[194:195], v[182:183], v[54:55], v[194:195]
	v_pk_fma_f32 v[196:197], v[180:181], v[54:55], v[196:197]
	v_pk_fma_f32 v[198:199], v[178:179], v[54:55], v[198:199]
	v_pk_fma_f32 v[200:201], v[176:177], v[54:55], v[200:201]
	v_pk_fma_f32 v[202:203], v[174:175], v[54:55], v[202:203]
	v_pk_fma_f32 v[204:205], v[172:173], v[54:55], v[204:205]
	v_pk_fma_f32 v[206:207], v[170:171], v[54:55], v[206:207]
	v_pk_fma_f32 v[208:209], v[168:169], v[54:55], v[208:209]
	v_pk_fma_f32 v[210:211], v[166:167], v[54:55], v[210:211]
	v_pk_fma_f32 v[212:213], v[164:165], v[54:55], v[212:213]
	v_pk_fma_f32 v[214:215], v[162:163], v[54:55], v[214:215]
	v_pk_fma_f32 v[216:217], v[160:161], v[54:55], v[216:217]
	v_pk_fma_f32 v[218:219], v[158:159], v[54:55], v[218:219]
	v_pk_fma_f32 v[220:221], v[156:157], v[54:55], v[220:221]
	v_pk_fma_f32 v[192:193], v[186:187], v[56:57], v[192:193]
	v_pk_fma_f32 v[194:195], v[184:185], v[56:57], v[194:195]
	v_pk_fma_f32 v[196:197], v[182:183], v[56:57], v[196:197]
	v_pk_fma_f32 v[198:199], v[180:181], v[56:57], v[198:199]
	v_pk_fma_f32 v[200:201], v[178:179], v[56:57], v[200:201]
	v_pk_fma_f32 v[202:203], v[176:177], v[56:57], v[202:203]
	v_pk_fma_f32 v[204:205], v[174:175], v[56:57], v[204:205]
	v_pk_fma_f32 v[206:207], v[172:173], v[56:57], v[206:207]
	v_pk_fma_f32 v[208:209], v[170:171], v[56:57], v[208:209]
	v_pk_fma_f32 v[210:211], v[168:169], v[56:57], v[210:211]
	v_pk_fma_f32 v[212:213], v[166:167], v[56:57], v[212:213]
	v_pk_fma_f32 v[214:215], v[164:165], v[56:57], v[214:215]
	v_pk_fma_f32 v[216:217], v[162:163], v[56:57], v[216:217]
	v_pk_fma_f32 v[218:219], v[160:161], v[56:57], v[218:219]
	v_pk_fma_f32 v[220:221], v[158:159], v[56:57], v[220:221]
	v_pk_fma_f32 v[194:195], v[186:187], v[58:59], v[194:195]
	v_pk_fma_f32 v[196:197], v[184:185], v[58:59], v[196:197]
	v_pk_fma_f32 v[198:199], v[182:183], v[58:59], v[198:199]
	v_pk_fma_f32 v[200:201], v[180:181], v[58:59], v[200:201]
	v_pk_fma_f32 v[202:203], v[178:179], v[58:59], v[202:203]
	v_pk_fma_f32 v[204:205], v[176:177], v[58:59], v[204:205]
	v_pk_fma_f32 v[206:207], v[174:175], v[58:59], v[206:207]
	v_pk_fma_f32 v[208:209], v[172:173], v[58:59], v[208:209]
	v_pk_fma_f32 v[210:211], v[170:171], v[58:59], v[210:211]
	v_pk_fma_f32 v[212:213], v[168:169], v[58:59], v[212:213]
	v_pk_fma_f32 v[214:215], v[166:167], v[58:59], v[214:215]
	v_pk_fma_f32 v[216:217], v[164:165], v[58:59], v[216:217]
	v_pk_fma_f32 v[218:219], v[162:163], v[58:59], v[218:219]
	v_pk_fma_f32 v[220:221], v[160:161], v[58:59], v[220:221]
	v_pk_fma_f32 v[196:197], v[186:187], v[60:61], v[196:197]
	v_pk_fma_f32 v[198:199], v[184:185], v[60:61], v[198:199]
	v_pk_fma_f32 v[200:201], v[182:183], v[60:61], v[200:201]
	v_pk_fma_f32 v[202:203], v[180:181], v[60:61], v[202:203]
	v_add_u32_e32 v26, s36, v80
	v_pk_fma_f32 v[204:205], v[178:179], v[60:61], v[204:205]
	v_pk_fma_f32 v[206:207], v[176:177], v[60:61], v[206:207]
	v_pk_fma_f32 v[208:209], v[174:175], v[60:61], v[208:209]
	v_pk_fma_f32 v[210:211], v[172:173], v[60:61], v[210:211]
	v_pk_fma_f32 v[212:213], v[170:171], v[60:61], v[212:213]
	v_pk_fma_f32 v[214:215], v[168:169], v[60:61], v[214:215]
	v_pk_fma_f32 v[216:217], v[166:167], v[60:61], v[216:217]
	v_pk_fma_f32 v[218:219], v[164:165], v[60:61], v[218:219]
	v_mov_b64_e32 v[24:25], s[62:63]
	v_pk_fma_f32 v[220:221], v[162:163], v[60:61], v[220:221]
	v_pk_fma_f32 v[198:199], v[186:187], v[62:63], v[198:199]
	v_pk_fma_f32 v[200:201], v[184:185], v[62:63], v[200:201]
	v_pk_fma_f32 v[202:203], v[182:183], v[62:63], v[202:203]
	v_pk_fma_f32 v[204:205], v[180:181], v[62:63], v[204:205]
	v_pk_fma_f32 v[206:207], v[178:179], v[62:63], v[206:207]
	v_pk_fma_f32 v[208:209], v[176:177], v[62:63], v[208:209]
	v_pk_fma_f32 v[210:211], v[174:175], v[62:63], v[210:211]
	v_lshl_add_u64 v[0:1], v[42:43], 0, s[12:13]
	v_pk_fma_f32 v[212:213], v[172:173], v[62:63], v[212:213]
	v_pk_fma_f32 v[214:215], v[170:171], v[62:63], v[214:215]
	v_pk_fma_f32 v[216:217], v[168:169], v[62:63], v[216:217]
	v_pk_fma_f32 v[218:219], v[166:167], v[62:63], v[218:219]
	v_pk_fma_f32 v[220:221], v[164:165], v[62:63], v[220:221]
	v_pk_fma_f32 v[200:201], v[186:187], v[64:65], v[200:201]
	v_pk_fma_f32 v[202:203], v[184:185], v[64:65], v[202:203]
	v_pk_fma_f32 v[204:205], v[182:183], v[64:65], v[204:205]
	v_lshl_add_u64 v[4:5], v[44:45], 0, s[12:13]
	v_pk_fma_f32 v[206:207], v[180:181], v[64:65], v[206:207]
	v_pk_fma_f32 v[208:209], v[178:179], v[64:65], v[208:209]
	v_pk_fma_f32 v[210:211], v[176:177], v[64:65], v[210:211]
; DI void conv_item(LAS unsigned char* lds, int item, const bf16_t* P, const float* cw, const float* cb, const float* lng, const float* lnb, bf16_t* MIX) {
;     ...
;         for (int i = 0; i < 32; ++i)
; #pragma unroll
;             for (int k = 0; k < 31; ++k) y[i] += w[k] * uw[i + k];
;     }
;     __syncthreads();
; #pragma unroll
;     for (int i = 0; i < 32; ++i) U[(tq * 32 + i) * 128 + c] = y[i];
;     __syncthreads();
;     {
;         const int ts = lane >> 4, cl = lane & 15, ca = 4 * cl, cb2 = 64 + 4 * cl;
;         const f32x4 ga = *(const f32x4*)(lng + cbase + ca), gb = *(const f32x4*)(lng + cbase + cb2);
;         const f32x4 ba = *(const f32x4*)(lnb + cbase + ca), bb = *(const f32x4*)(lnb + cbase + cb2);
; #pragma unroll
;         for (int it = 0; it < 4; ++it) {
;             const int t = wid * 16 + it * 4 + ts;
;             const size_t row = (size_t)(tt0 + t);
;             const u32x2 za = *(const u32x2*)(P + row * LDP + 2048 + cbase + ca), zb = *(const u32x2*)(P + row * LDP + 2048 + cbase + cb2);
	v_pk_fma_f32 v[212:213], v[174:175], v[64:65], v[212:213]
	v_pk_fma_f32 v[214:215], v[172:173], v[64:65], v[214:215]
	v_pk_fma_f32 v[216:217], v[170:171], v[64:65], v[216:217]
	v_pk_fma_f32 v[218:219], v[168:169], v[64:65], v[218:219]
	v_pk_fma_f32 v[220:221], v[166:167], v[64:65], v[220:221]
	s_lshl_b32 s12, s37, 1
	v_pk_fma_f32 v[202:203], v[186:187], v[66:67], v[202:203]
	v_pk_fma_f32 v[204:205], v[184:185], v[66:67], v[204:205]
	v_pk_fma_f32 v[206:207], v[182:183], v[66:67], v[206:207]
	v_pk_fma_f32 v[208:209], v[180:181], v[66:67], v[208:209]
	v_pk_fma_f32 v[210:211], v[178:179], v[66:67], v[210:211]
	v_pk_fma_f32 v[212:213], v[176:177], v[66:67], v[212:213]
	v_pk_fma_f32 v[214:215], v[174:175], v[66:67], v[214:215]
	v_pk_fma_f32 v[216:217], v[172:173], v[66:67], v[216:217]
	v_mad_i64_i32 v[2:3], s[26:27], v26, s30, v[24:25]
	v_pk_fma_f32 v[218:219], v[170:171], v[66:67], v[218:219]
	v_pk_fma_f32 v[220:221], v[168:169], v[66:67], v[220:221]
	v_pk_fma_f32 v[204:205], v[186:187], v[92:93], v[204:205]
	v_pk_fma_f32 v[206:207], v[184:185], v[92:93], v[206:207]
	v_pk_fma_f32 v[208:209], v[182:183], v[92:93], v[208:209]
	v_pk_fma_f32 v[210:211], v[180:181], v[92:93], v[210:211]
	v_pk_fma_f32 v[212:213], v[178:179], v[92:93], v[212:213]
	v_pk_fma_f32 v[214:215], v[176:177], v[92:93], v[214:215]
	v_lshl_add_u64 v[2:3], v[2:3], 0, s[12:13]
	v_pk_fma_f32 v[216:217], v[174:175], v[92:93], v[216:217]
	v_pk_fma_f32 v[218:219], v[172:173], v[92:93], v[218:219]
	v_pk_fma_f32 v[220:221], v[170:171], v[92:93], v[220:221]
	v_pk_fma_f32 v[206:207], v[186:187], v[94:95], v[206:207]
	v_pk_fma_f32 v[208:209], v[184:185], v[94:95], v[208:209]
	v_pk_fma_f32 v[210:211], v[182:183], v[94:95], v[210:211]
	v_pk_fma_f32 v[212:213], v[180:181], v[94:95], v[212:213]
	v_pk_fma_f32 v[214:215], v[178:179], v[94:95], v[214:215]
	v_mov_b32_e32 v47, v41
	v_pk_fma_f32 v[216:217], v[176:177], v[94:95], v[216:217]
	v_pk_fma_f32 v[218:219], v[174:175], v[94:95], v[218:219]
	v_pk_fma_f32 v[220:221], v[172:173], v[94:95], v[220:221]
	v_pk_fma_f32 v[208:209], v[186:187], v[96:97], v[208:209]
	v_pk_fma_f32 v[210:211], v[184:185], v[96:97], v[210:211]
	v_pk_fma_f32 v[212:213], v[182:183], v[96:97], v[212:213]
	v_pk_fma_f32 v[214:215], v[180:181], v[96:97], v[214:215]
	v_pk_fma_f32 v[216:217], v[178:179], v[96:97], v[216:217]
	v_lshl_add_u64 v[2:3], v[2:3], 0, v[46:47]
	v_pk_fma_f32 v[218:219], v[176:177], v[96:97], v[218:219]
	v_pk_fma_f32 v[220:221], v[174:175], v[96:97], v[220:221]
	v_pk_fma_f32 v[210:211], v[186:187], v[98:99], v[210:211]
	v_pk_fma_f32 v[212:213], v[184:185], v[98:99], v[212:213]
	v_pk_fma_f32 v[214:215], v[182:183], v[98:99], v[214:215]
	v_pk_fma_f32 v[216:217], v[180:181], v[98:99], v[216:217]
	v_pk_fma_f32 v[218:219], v[178:179], v[98:99], v[218:219]
	v_pk_fma_f32 v[220:221], v[176:177], v[98:99], v[220:221]
	v_add_co_u32_e32 v6, vcc, s31, v2
	v_pk_fma_f32 v[212:213], v[186:187], v[100:101], v[212:213]
	v_pk_fma_f32 v[214:215], v[184:185], v[100:101], v[214:215]
	v_pk_fma_f32 v[216:217], v[182:183], v[100:101], v[216:217]
	v_pk_fma_f32 v[218:219], v[180:181], v[100:101], v[218:219]
	v_pk_fma_f32 v[220:221], v[178:179], v[100:101], v[220:221]
	v_pk_fma_f32 v[214:215], v[186:187], v[102:103], v[214:215]
	v_pk_fma_f32 v[216:217], v[184:185], v[102:103], v[216:217]
	v_pk_fma_f32 v[218:219], v[182:183], v[102:103], v[218:219]
	v_addc_co_u32_e32 v7, vcc, 0, v3, vcc
	v_pk_fma_f32 v[220:221], v[180:181], v[102:103], v[220:221]
	v_pk_fma_f32 v[216:217], v[186:187], v[104:105], v[216:217]
	v_pk_fma_f32 v[218:219], v[184:185], v[104:105], v[218:219]
	v_pk_fma_f32 v[220:221], v[182:183], v[104:105], v[220:221]
	v_pk_fma_f32 v[218:219], v[186:187], v[106:107], v[218:219]
	v_pk_fma_f32 v[220:221], v[184:185], v[106:107], v[220:221]
	v_pk_fma_f32 v[220:221], v[186:187], v[108:109], v[220:221]
	global_load_dwordx2 v[126:127], v[6:7], off
	global_load_dwordx2 v[128:129], v[6:7], off offset:128
	s_mov_b32 vcc_hi, 0
	s_mov_b32 vcc_lo, 0xa200
	v_lshl_add_u64 v[132:133], v[6:7], 0, vcc
	global_load_dwordx2 v[130:131], v[132:133], off
	global_load_dwordx2 v[132:133], v[132:133], off offset:128
	s_mov_b32 vcc_lo, 0x14400
	v_lshl_add_u64 v[136:137], v[6:7], 0, vcc
	global_load_dwordx2 v[134:135], v[136:137], off
	global_load_dwordx2 v[136:137], v[136:137], off offset:128
	s_mov_b32 vcc_lo, 0x1e600
	v_lshl_add_u64 v[140:141], v[6:7], 0, vcc
	global_load_dwordx2 v[138:139], v[140:141], off
	global_load_dwordx2 v[140:141], v[140:141], off offset:128
	ds_write_b64 v251, v[190:191]
	ds_write_b64 v251, v[192:193] offset:512
	ds_write_b64 v251, v[194:195] offset:1024
	ds_write_b64 v251, v[196:197] offset:1536
	ds_write_b64 v251, v[198:199] offset:2048
	ds_write_b64 v251, v[200:201] offset:2560
	ds_write_b64 v251, v[202:203] offset:3072
	ds_write_b64 v251, v[204:205] offset:3584
	ds_write_b64 v251, v[206:207] offset:4096
	ds_write_b64 v251, v[208:209] offset:4608
	ds_write_b64 v251, v[210:211] offset:5120
	ds_write_b64 v251, v[212:213] offset:5632
	ds_write_b64 v251, v[214:215] offset:6144
	ds_write_b64 v251, v[216:217] offset:6656
	ds_write_b64 v251, v[218:219] offset:7168
	ds_write_b64 v251, v[220:221] offset:7680
	s_waitcnt lgkmcnt(0)
	s_barrier
; #define LAS __attribute__((address_space(3)))
; DI float dot4(const f32x4 a) { return (a[0] * a[0] + a[1] * a[1]) + (a[2] * a[2] + a[3] * a[3]); }
; DI void conv_item(LAS unsigned char* lds, int item, const bf16_t* P, const float* cw, const float* cb, const float* lng, const float* lnb, bf16_t* MIX) {
;     ...
;         for (int it = 0; it < 4; ++it) {
;             const int t = wid * 16 + it * 4 + ts;
;             const size_t row = (size_t)(tt0 + t);
;             const u32x2 za = *(const u32x2*)(P + row * LDP + 2048 + cbase + ca), zb = *(const u32x2*)(P + row * LDP + 2048 + cbase + cb2);
;             f32x4 va = *(LAS f32x4*)(U + t * 128 + ca), vb = *(LAS f32x4*)(U + t * 128 + cb2);
;             float sm = ((va[0] + va[1]) + (va[2] + va[3])) + ((vb[0] + vb[1]) + (vb[2] + vb[3]));
;             sm += __shfl_xor(sm, 1); sm += __shfl_xor(sm, 2); sm += __shfl_xor(sm, 4); sm += __shfl_xor(sm, 8);
;             const float mu = sm * (1.f / 128.f);
;             va = va - mu; vb = vb - mu;
;             float sq = dot4(va) + dot4(vb);
;             sq += __shfl_xor(sq, 1); sq += __shfl_xor(sq, 2); sq += __shfl_xor(sq, 4); sq += __shfl_xor(sq, 8);
;             const float rstd = rsqrtf(sq * (1.f / 128.f) + EPS_);
	s_waitcnt vmcnt(6)
	v_mov_b32_e32 v28, v126
	v_mov_b32_e32 v29, v127
	v_lshl_add_u64 v[2:3], v[2:3], 0, s[18:19]
	ds_read_b128 v[20:23], v85
	ds_read_b128 v[16:19], v85 offset:256
	v_mov_b32_e32 v36, v128
	v_mov_b32_e32 v37, v129
	s_add_u32 s26, s80, s12
	v_ashrrev_i32_e32 v27, 31, v26
	s_waitcnt lgkmcnt(1)
	v_mov_b32_e32 v6, v20
	s_waitcnt lgkmcnt(0)
	v_mov_b32_e32 v7, v16
	v_mov_b32_e32 v8, v21
	v_mov_b32_e32 v9, v17
	v_pk_add_f32 v[6:7], v[6:7], v[8:9]
	v_mov_b32_e32 v8, v22
	v_mov_b32_e32 v9, v18
	v_mov_b32_e32 v10, v23
	v_mov_b32_e32 v11, v19
	v_pk_add_f32 v[8:9], v[8:9], v[10:11]
	s_addc_u32 s27, s81, 0
	v_pk_add_f32 v[6:7], v[6:7], v[8:9]
	s_add_i32 s35, s35, s58
	v_add_f32_e32 v6, v6, v7
	ds_bpermute_b32 v7, v81, v6
	s_add_i32 s28, s28, s29
	s_waitcnt lgkmcnt(0)
	v_add_f32_e32 v2, v6, v7
	ds_bpermute_b32 v3, v82, v2
	s_waitcnt lgkmcnt(0)
	v_add_f32_e32 v6, v2, v3
	ds_bpermute_b32 v7, v83, v6
	global_load_dwordx4 v[8:11], v[0:1], off
	s_nop 0
	global_load_dwordx4 v[0:3], v[0:1], off offset:256
	s_waitcnt lgkmcnt(0)
	v_add_f32_e32 v30, v6, v7
	ds_bpermute_b32 v31, v84, v30
	global_load_dwordx4 v[12:15], v[4:5], off
	s_nop 0
	global_load_dwordx4 v[4:7], v[4:5], off offset:256
	s_waitcnt lgkmcnt(0)
	v_add_f32_e32 v30, v30, v31
	v_fmamk_f32 v21, v30, 0xbc000000, v21
	v_fmamk_f32 v17, v30, 0xbc000000, v17
	v_fmamk_f32 v39, v30, 0xbc000000, v23
	v_fmamk_f32 v38, v30, 0xbc000000, v22
	v_fmac_f32_e32 v20, 0xbc000000, v30
	v_fmamk_f32 v23, v30, 0xbc000000, v19
	v_fmamk_f32 v22, v30, 0xbc000000, v18
	v_fmac_f32_e32 v16, 0xbc000000, v30
	v_mov_b32_e32 v30, v21
	v_mov_b32_e32 v31, v17
	v_mov_b32_e32 v18, v20
	v_mov_b32_e32 v19, v16
	v_pk_mul_f32 v[30:31], v[30:31], v[30:31]
	v_mov_b32_e32 v32, v39
	v_mov_b32_e32 v33, v23
	v_pk_fma_f32 v[18:19], v[18:19], v[18:19], v[30:31]
	v_mov_b32_e32 v30, v38
	v_mov_b32_e32 v31, v22
	v_pk_mul_f32 v[32:33], v[32:33], v[32:33]
	s_waitcnt vmcnt(5)
	v_lshlrev_b32_e32 v50, 16, v28
	v_and_b32_e32 v51, 0xffff0000, v28
	v_mul_f32_e32 v28, 0xbfb8aa3b, v50
	v_pk_fma_f32 v[30:31], v[30:31], v[30:31], v[32:33]
	v_exp_f32_e32 v28, v28
	v_mul_f32_e32 v32, 0xbfb8aa3b, v51
	v_exp_f32_e32 v32, v32
	v_pk_add_f32 v[18:19], v[18:19], v[30:31]
	v_add_f32_e32 v28, 1.0, v28
	v_rcp_f32_e32 v52, v28
	v_add_f32_e32 v28, 1.0, v32
	v_rcp_f32_e32 v53, v28
	v_lshlrev_b32_e32 v54, 16, v29
	v_and_b32_e32 v55, 0xffff0000, v29
	ds_read_b128 v[28:31], v87
	ds_read_b128 v[32:35], v87 offset:256
	v_mul_f32_e32 v40, 0xbfb8aa3b, v54
	v_exp_f32_e32 v40, v40
	v_mul_f32_e32 v49, 0xbfb8aa3b, v55
	s_waitcnt lgkmcnt(1)
	v_mov_b32_e32 v56, v28
	s_waitcnt lgkmcnt(0)
	v_mov_b32_e32 v57, v32
	v_mov_b32_e32 v58, v29
	v_mov_b32_e32 v59, v33
	v_pk_add_f32 v[56:57], v[56:57], v[58:59]
	v_mov_b32_e32 v58, v30
	v_mov_b32_e32 v59, v34
	v_mov_b32_e32 v60, v31
	v_mov_b32_e32 v61, v35
	v_pk_add_f32 v[58:59], v[58:59], v[60:61]
	v_exp_f32_e32 v49, v49
	v_pk_add_f32 v[56:57], v[56:57], v[58:59]
	v_add_f32_e32 v40, 1.0, v40
	v_add_f32_e32 v58, v56, v57
	ds_bpermute_b32 v59, v81, v58
	v_rcp_f32_e32 v56, v40
	v_add_f32_e32 v40, 1.0, v49
	v_rcp_f32_e32 v57, v40
	v_pk_mul_f32 v[50:51], v[52:53], v[50:51]
	s_waitcnt lgkmcnt(0)
	v_add_f32_e32 v40, v58, v59
	ds_bpermute_b32 v49, v82, v40
	s_waitcnt vmcnt(4)
	v_lshlrev_b32_e32 v58, 16, v36
	v_mul_f32_e32 v59, 0xbfb8aa3b, v58
	v_exp_f32_e32 v60, v59
	v_and_b32_e32 v59, 0xffff0000, v36
	s_waitcnt lgkmcnt(0)
	v_add_f32_e32 v36, v40, v49
	ds_bpermute_b32 v40, v83, v36
	v_add_f32_e32 v49, 1.0, v60
	v_mul_f32_e32 v60, 0xbfb8aa3b, v59
	v_exp_f32_e32 v61, v60
	v_rcp_f32_e32 v60, v49
	s_waitcnt lgkmcnt(0)
	v_add_f32_e32 v40, v36, v40
	ds_bpermute_b32 v49, v84, v40
	v_add_f32_e32 v36, 1.0, v61
	v_rcp_f32_e32 v61, v36
	v_pk_mul_f32 v[52:53], v[56:57], v[54:55]
	v_lshlrev_b32_e32 v36, 16, v37
	s_waitcnt lgkmcnt(0)
	v_add_f32_e32 v40, v40, v49
	v_fmamk_f32 v29, v40, 0xbc000000, v29
	v_fmamk_f32 v33, v40, 0xbc000000, v33
	v_fmamk_f32 v31, v40, 0xbc000000, v31
	v_fmac_f32_e32 v28, 0xbc000000, v40
	v_fmamk_f32 v35, v40, 0xbc000000, v35
	v_fmac_f32_e32 v32, 0xbc000000, v40
	v_mov_b32_e32 v64, v29
	v_mov_b32_e32 v65, v33
	v_fmamk_f32 v30, v40, 0xbc000000, v30
	v_fmamk_f32 v34, v40, 0xbc000000, v34
	v_mov_b32_e32 v62, v28
	v_mov_b32_e32 v63, v32
	v_pk_mul_f32 v[64:65], v[64:65], v[64:65]
	v_mov_b32_e32 v66, v31
	v_mov_b32_e32 v67, v35
	v_pk_fma_f32 v[62:63], v[62:63], v[62:63], v[64:65]
	v_mov_b32_e32 v64, v30
	v_mov_b32_e32 v65, v34
	v_pk_mul_f32 v[66:67], v[66:67], v[66:67]
	v_pk_mul_f32 v[54:55], v[60:61], v[58:59]
	v_pk_fma_f32 v[64:65], v[64:65], v[64:65], v[66:67]
	v_and_b32_e32 v37, 0xffff0000, v37
	v_pk_add_f32 v[62:63], v[62:63], v[64:65]
	v_mov_b32_e32 v65, v18
	v_mov_b32_e32 v64, v62
	v_mov_b32_e32 v18, v63
	v_pk_add_f32 v[18:19], v[64:65], v[18:19]
	ds_bpermute_b32 v63, v81, v19
	ds_bpermute_b32 v62, v81, v18
	v_mul_f32_e32 v40, 0xbfb8aa3b, v36
	v_exp_f32_e32 v40, v40
	v_mul_f32_e32 v49, 0xbfb8aa3b, v37
	v_exp_f32_e32 v49, v49
	s_waitcnt lgkmcnt(0)
	v_pk_add_f32 v[18:19], v[18:19], v[62:63]
	ds_bpermute_b32 v63, v82, v19
	ds_bpermute_b32 v62, v82, v18
	v_add_f32_e32 v40, 1.0, v40
	v_rcp_f32_e32 v64, v40
	v_add_f32_e32 v40, 1.0, v49
	v_rcp_f32_e32 v65, v40
	s_waitcnt lgkmcnt(0)
	v_pk_add_f32 v[18:19], v[18:19], v[62:63]
	ds_bpermute_b32 v63, v83, v19
	ds_bpermute_b32 v62, v83, v18
	v_pk_mul_f32 v[36:37], v[64:65], v[36:37]
	s_waitcnt lgkmcnt(0)
	v_pk_add_f32 v[56:57], v[18:19], v[62:63]
	ds_bpermute_b32 v59, v84, v57
	ds_bpermute_b32 v58, v84, v56
	v_lshlrev_b64 v[18:19], 12, v[26:27]
	v_mov_b64_e32 v[26:27], s[22:23]
	v_lshl_add_u64 v[18:19], s[26:27], 0, v[18:19]
	v_lshl_add_u64 v[60:61], v[18:19], 0, v[46:47]
	s_waitcnt lgkmcnt(0)
; DI float siluf_(float x) { return x * frcp(1.f + fexp(-x)); }
; DI u32x2 pack4(const f32x4 a) { u32x2 w; w.x = pk2(a[0], a[1]); w.y = pk2(a[2], a[3]); return w; }
; DI float dot4(const f32x4 a) { return (a[0] * a[0] + a[1] * a[1]) + (a[2] * a[2] + a[3] * a[3]); }
; DI void conv_item(LAS unsigned char* lds, int item, const bf16_t* P, const float* cw, const float* cb, const float* lng, const float* lnb, bf16_t* MIX) {
;     ...
;             float sq = dot4(va) + dot4(vb);
;             sq += __shfl_xor(sq, 1); sq += __shfl_xor(sq, 2); sq += __shfl_xor(sq, 4); sq += __shfl_xor(sq, 8);
;             const float rstd = rsqrtf(sq * (1.f / 128.f) + EPS_);
;             f32x4 oa = va * rstd * ga + ba, ob = vb * rstd * gb + bb;
;             oa[0] = siluf_(oa[0]) * siluf_(bflo(za.x)); oa[1] = siluf_(oa[1]) * siluf_(bfhi(za.x)); oa[2] = siluf_(oa[2]) * siluf_(bflo(za.y)); oa[3] = siluf_(oa[3]) * siluf_(bfhi(za.y));
;             ob[0] = siluf_(ob[0]) * siluf_(bflo(zb.x)); ob[1] = siluf_(ob[1]) * siluf_(bfhi(zb.x)); ob[2] = siluf_(ob[2]) * siluf_(bflo(zb.y)); ob[3] = siluf_(ob[3]) * siluf_(bfhi(zb.y));
;             *(u32x2*)(MIX + row * DM + cbase + ca) = pack4(oa); *(u32x2*)(MIX + row * DM + cbase + cb2) = pack4(ob);
	v_pk_add_f32 v[56:57], v[56:57], v[58:59]
	v_add_u32_e32 v18, s36, v86
	v_pk_fma_f32 v[56:57], v[56:57], s[20:21], v[26:27] op_sel_hi:[1,0,0]
	v_mad_i64_i32 v[58:59], s[38:39], v18, s30, v[24:25]
	v_mul_f32_e32 v19, 0x4b800000, v57
	v_cmp_gt_f32_e32 vcc, s34, v57
	v_lshl_add_u64 v[58:59], v[58:59], 0, s[12:13]
	v_lshl_add_u64 v[58:59], v[58:59], 0, v[46:47]
	v_cndmask_b32_e32 v19, v57, v19, vcc
	v_rsq_f32_e32 v19, v19
	s_nop 0
	v_mul_f32_e32 v40, 0x45800000, v19
	v_cndmask_b32_e32 v40, v19, v40, vcc
	v_pk_mul_f32 v[20:21], v[20:21], v[40:41] op_sel_hi:[1,0]
	v_pk_mul_f32 v[38:39], v[38:39], v[40:41] op_sel_hi:[1,0]
	s_waitcnt vmcnt(1)
	v_pk_fma_f32 v[20:21], v[8:9], v[20:21], v[12:13]
	v_pk_fma_f32 v[38:39], v[10:11], v[38:39], v[14:15]
	v_mul_f32_e32 v19, 0xbfb8aa3b, v20
	v_exp_f32_e32 v19, v19
	v_mul_f32_e32 v49, 0xbfb8aa3b, v21
	v_exp_f32_e32 v49, v49
	v_pk_mul_f32 v[16:17], v[16:17], v[40:41] op_sel_hi:[1,0]
	v_add_f32_e32 v19, 1.0, v19
	v_rcp_f32_e32 v62, v19
	v_add_f32_e32 v19, 1.0, v49
	v_rcp_f32_e32 v63, v19
	v_mul_f32_e32 v19, 0xbfb8aa3b, v38
	v_pk_mul_f32 v[22:23], v[22:23], v[40:41] op_sel_hi:[1,0]
	v_exp_f32_e32 v19, v19
	v_mul_f32_e32 v40, 0xbfb8aa3b, v39
	v_exp_f32_e32 v40, v40
	v_pk_mul_f32 v[20:21], v[20:21], v[62:63]
	v_add_f32_e32 v19, 1.0, v19
	s_waitcnt vmcnt(0)
	v_pk_fma_f32 v[16:17], v[0:1], v[16:17], v[4:5]
	v_pk_mul_f32 v[20:21], v[50:51], v[20:21]
	v_rcp_f32_e32 v50, v19
	v_add_f32_e32 v19, 1.0, v40
	v_rcp_f32_e32 v51, v19
	v_mul_f32_e32 v19, 0xbfb8aa3b, v16
	v_exp_f32_e32 v19, v19
	v_mul_f32_e32 v40, 0xbfb8aa3b, v17
	v_exp_f32_e32 v40, v40
	v_pk_fma_f32 v[22:23], v[2:3], v[22:23], v[6:7]
	v_add_f32_e32 v19, 1.0, v19
	v_pk_mul_f32 v[38:39], v[38:39], v[50:51]
	v_rcp_f32_e32 v50, v19
	v_add_f32_e32 v19, 1.0, v40
	v_mul_f32_e32 v40, 0xbfb8aa3b, v22
	v_exp_f32_e32 v40, v40
	v_mul_f32_e32 v49, 0xbfb8aa3b, v23
	v_exp_f32_e32 v49, v49
	v_rcp_f32_e32 v51, v19
	v_add_f32_e32 v19, 1.0, v40
	v_rcp_f32_e32 v62, v19
	v_add_f32_e32 v19, 1.0, v49
	v_rcp_f32_e32 v63, v19
	v_pk_mul_f32 v[16:17], v[16:17], v[50:51]
	v_pk_mul_f32 v[38:39], v[52:53], v[38:39]
	v_pk_mul_f32 v[16:17], v[54:55], v[16:17]
	v_pk_mul_f32 v[22:23], v[22:23], v[62:63]
	v_cvt_pk_bf16_f32 v16, v16, v17
	v_pk_mul_f32 v[22:23], v[36:37], v[22:23]
	v_cvt_pk_bf16_f32 v20, v20, v21
	v_cvt_pk_bf16_f32 v17, v22, v23
	v_cvt_pk_bf16_f32 v21, v38, v39
	global_store_dwordx2 v[60:61], v[16:17], off offset:128
	v_add_co_u32_e32 v16, vcc, s31, v58
	global_store_dwordx2 v[60:61], v[20:21], off
	s_nop 0
	v_addc_co_u32_e32 v17, vcc, 0, v59, vcc
	v_mov_b32_e32 v16, v130
	v_mov_b32_e32 v17, v131
	v_lshl_add_u64 v[20:21], v[58:59], 0, s[18:19]
	v_mov_b32_e32 v20, v132
	v_mov_b32_e32 v21, v133
	v_mul_f32_e32 v19, 0x4b800000, v56
	v_cmp_gt_f32_e32 vcc, s34, v56
	s_nop 0
	v_lshlrev_b32_e32 v36, 16, v16
	v_cndmask_b32_e32 v19, v56, v19, vcc
	v_rsq_f32_e32 v22, v19
	v_mul_f32_e32 v37, 0xbfb8aa3b, v36
	v_exp_f32_e32 v38, v37
	v_and_b32_e32 v37, 0xffff0000, v16
	v_mul_f32_e32 v23, 0x45800000, v22
	v_cndmask_b32_e32 v22, v22, v23, vcc
	v_pk_mul_f32 v[28:29], v[28:29], v[22:23] op_sel_hi:[1,0]
	v_pk_mul_f32 v[30:31], v[30:31], v[22:23] op_sel_hi:[1,0]
	v_pk_fma_f32 v[28:29], v[8:9], v[28:29], v[12:13]
	v_pk_mul_f32 v[32:33], v[32:33], v[22:23] op_sel_hi:[1,0]
	v_pk_mul_f32 v[22:23], v[34:35], v[22:23] op_sel_hi:[1,0]
	v_mul_f32_e32 v34, 0xbfb8aa3b, v28
	v_mul_f32_e32 v35, 0xbfb8aa3b, v29
	v_exp_f32_e32 v34, v34
	v_exp_f32_e32 v35, v35
	v_pk_fma_f32 v[30:31], v[10:11], v[30:31], v[14:15]
	v_mul_f32_e32 v16, 0xbfb8aa3b, v37
	v_add_f32_e32 v34, 1.0, v34
	v_add_f32_e32 v35, 1.0, v35
	v_rcp_f32_e32 v34, v34
	v_rcp_f32_e32 v35, v35
	v_exp_f32_e32 v16, v16
	v_pk_fma_f32 v[32:33], v[0:1], v[32:33], v[4:5]
	v_add_f32_e32 v38, 1.0, v38
	v_pk_mul_f32 v[28:29], v[28:29], v[34:35]
	v_mul_f32_e32 v34, 0xbfb8aa3b, v30
	v_exp_f32_e32 v34, v34
	v_mul_f32_e32 v35, 0xbfb8aa3b, v31
	v_exp_f32_e32 v35, v35
	v_add_f32_e32 v16, 1.0, v16
	v_rcp_f32_e32 v39, v16
	v_add_f32_e32 v16, 1.0, v34
	v_lshlrev_b32_e32 v34, 16, v17
	v_add_f32_e32 v40, 1.0, v35
	v_and_b32_e32 v35, 0xffff0000, v17
	v_mul_f32_e32 v17, 0xbfb8aa3b, v34
	v_exp_f32_e32 v49, v17
	v_mul_f32_e32 v17, 0xbfb8aa3b, v35
	v_exp_f32_e32 v51, v17
	v_rcp_f32_e32 v17, v40
	v_add_f32_e32 v40, 1.0, v49
	v_rcp_f32_e32 v50, v40
	v_add_f32_e32 v40, 1.0, v51
	v_rcp_f32_e32 v16, v16
	v_rcp_f32_e32 v51, v40
	v_rcp_f32_e32 v38, v38
	v_pk_fma_f32 v[22:23], v[2:3], v[22:23], v[6:7]
	v_pk_mul_f32 v[16:17], v[30:31], v[16:17]
	v_pk_mul_f32 v[30:31], v[50:51], v[34:35]
	v_mul_f32_e32 v34, 0xbfb8aa3b, v32
	v_mul_f32_e32 v35, 0xbfb8aa3b, v33
	v_exp_f32_e32 v34, v34
	v_exp_f32_e32 v35, v35
	v_pk_mul_f32 v[16:17], v[30:31], v[16:17]
	v_pk_mul_f32 v[36:37], v[38:39], v[36:37]
	v_add_f32_e32 v30, 1.0, v34
	v_add_f32_e32 v31, 1.0, v35
	v_rcp_f32_e32 v30, v30
	v_rcp_f32_e32 v31, v31
	s_nop 0
	v_lshlrev_b32_e32 v34, 16, v20
	v_mul_f32_e32 v35, 0xbfb8aa3b, v34
	v_pk_mul_f32 v[28:29], v[36:37], v[28:29]
	v_exp_f32_e32 v36, v35
	v_and_b32_e32 v35, 0xffff0000, v20
	v_mul_f32_e32 v20, 0xbfb8aa3b, v35
	v_exp_f32_e32 v20, v20
	v_pk_mul_f32 v[30:31], v[32:33], v[30:31]
	v_mul_f32_e32 v32, 0xbfb8aa3b, v22
	v_exp_f32_e32 v32, v32
	v_mul_f32_e32 v33, 0xbfb8aa3b, v23
	v_exp_f32_e32 v33, v33
	v_add_f32_e32 v20, 1.0, v20
	v_rcp_f32_e32 v37, v20
	v_add_f32_e32 v20, 1.0, v32
	v_lshlrev_b32_e32 v32, 16, v21
	v_add_f32_e32 v38, 1.0, v33
	v_and_b32_e32 v33, 0xffff0000, v21
	v_mul_f32_e32 v21, 0xbfb8aa3b, v32
	v_exp_f32_e32 v39, v21
	v_mul_f32_e32 v21, 0xbfb8aa3b, v33
	v_exp_f32_e32 v40, v21
	v_rcp_f32_e32 v21, v38
	v_add_f32_e32 v38, 1.0, v39
	v_add_f32_e32 v36, 1.0, v36
	v_add_f32_e32 v39, 1.0, v40
	v_rcp_f32_e32 v20, v20
	v_rcp_f32_e32 v38, v38
	v_rcp_f32_e32 v39, v39
	v_rcp_f32_e32 v36, v36
	v_ashrrev_i32_e32 v19, 31, v18
	v_pk_mul_f32 v[20:21], v[22:23], v[20:21]
	v_pk_mul_f32 v[22:23], v[38:39], v[32:33]
	v_pk_mul_f32 v[34:35], v[36:37], v[34:35]
	v_pk_mul_f32 v[20:21], v[22:23], v[20:21]
	v_cvt_pk_bf16_f32 v23, v16, v17
	v_lshlrev_b64 v[16:17], 12, v[18:19]
	v_pk_mul_f32 v[30:31], v[34:35], v[30:31]
	v_lshl_add_u64 v[16:17], s[26:27], 0, v[16:17]
	v_cvt_pk_bf16_f32 v22, v28, v29
	v_lshl_add_u64 v[16:17], v[16:17], 0, v[46:47]
	v_cvt_pk_bf16_f32 v18, v30, v31
	v_cvt_pk_bf16_f32 v19, v20, v21
	v_add_u32_e32 v28, s36, v88
	global_store_dwordx2 v[16:17], v[22:23], off
	global_store_dwordx2 v[16:17], v[18:19], off offset:128
	v_mad_i64_i32 v[16:17], s[38:39], v28, s30, v[24:25]
	v_lshl_add_u64 v[16:17], v[16:17], 0, s[12:13]
	v_lshl_add_u64 v[30:31], v[16:17], 0, v[46:47]
	v_add_co_u32_e32 v16, vcc, s31, v30
	s_nop 1
	v_addc_co_u32_e32 v17, vcc, 0, v31, vcc
	v_mov_b32_e32 v32, v134
	v_mov_b32_e32 v33, v135
	ds_read_b128 v[20:23], v89
	ds_read_b128 v[16:19], v89 offset:256
	v_lshl_add_u64 v[30:31], v[30:31], 0, s[18:19]
	s_waitcnt lgkmcnt(1)
; #define LAS __attribute__((address_space(3)))
; DI float dot4(const f32x4 a) { return (a[0] * a[0] + a[1] * a[1]) + (a[2] * a[2] + a[3] * a[3]); }
; DI void conv_item(LAS unsigned char* lds, int item, const bf16_t* P, const float* cw, const float* cb, const float* lng, const float* lnb, bf16_t* MIX) {
;     ...
;         for (int it = 0; it < 4; ++it) {
;             const int t = wid * 16 + it * 4 + ts;
;             const size_t row = (size_t)(tt0 + t);
;             const u32x2 za = *(const u32x2*)(P + row * LDP + 2048 + cbase + ca), zb = *(const u32x2*)(P + row * LDP + 2048 + cbase + cb2);
;             f32x4 va = *(LAS f32x4*)(U + t * 128 + ca), vb = *(LAS f32x4*)(U + t * 128 + cb2);
;             float sm = ((va[0] + va[1]) + (va[2] + va[3])) + ((vb[0] + vb[1]) + (vb[2] + vb[3]));
;             sm += __shfl_xor(sm, 1); sm += __shfl_xor(sm, 2); sm += __shfl_xor(sm, 4); sm += __shfl_xor(sm, 8);
;             const float mu = sm * (1.f / 128.f);
;             va = va - mu; vb = vb - mu;
;             float sq = dot4(va) + dot4(vb);
;             sq += __shfl_xor(sq, 1); sq += __shfl_xor(sq, 2); sq += __shfl_xor(sq, 4); sq += __shfl_xor(sq, 8);
;             const float rstd = rsqrtf(sq * (1.f / 128.f) + EPS_);
	v_mov_b32_e32 v34, v20
	s_waitcnt lgkmcnt(0)
	v_mov_b32_e32 v35, v16
	v_mov_b32_e32 v36, v21
	v_mov_b32_e32 v37, v17
	v_pk_add_f32 v[34:35], v[34:35], v[36:37]
	v_mov_b32_e32 v36, v22
	v_mov_b32_e32 v37, v18
	v_mov_b32_e32 v38, v23
	v_mov_b32_e32 v39, v19
	v_pk_add_f32 v[36:37], v[36:37], v[38:39]
	v_mov_b32_e32 v38, v136
	v_mov_b32_e32 v39, v137
	v_pk_add_f32 v[34:35], v[34:35], v[36:37]
	s_nop 0
	v_lshlrev_b32_e32 v52, 16, v32
	v_add_f32_e32 v29, v34, v35
	ds_bpermute_b32 v34, v81, v29
	v_and_b32_e32 v53, 0xffff0000, v32
	v_mul_f32_e32 v32, 0xbfb8aa3b, v52
	v_exp_f32_e32 v32, v32
	v_lshlrev_b32_e32 v56, 16, v33
	s_waitcnt lgkmcnt(0)
	v_add_f32_e32 v29, v29, v34
	ds_bpermute_b32 v30, v82, v29
	v_and_b32_e32 v57, 0xffff0000, v33
	v_mul_f32_e32 v40, 0xbfb8aa3b, v56
	v_exp_f32_e32 v40, v40
	v_mul_f32_e32 v49, 0xbfb8aa3b, v57
	s_waitcnt lgkmcnt(0)
	v_add_f32_e32 v29, v29, v30
	ds_bpermute_b32 v30, v83, v29
	v_exp_f32_e32 v49, v49
	v_add_f32_e32 v40, 1.0, v40
	s_waitcnt lgkmcnt(0)
	v_add_f32_e32 v30, v29, v30
	ds_bpermute_b32 v31, v84, v30
	v_ashrrev_i32_e32 v29, 31, v28
	s_waitcnt lgkmcnt(0)
	v_add_f32_e32 v30, v30, v31
	v_fmamk_f32 v21, v30, 0xbc000000, v21
	v_fmamk_f32 v17, v30, 0xbc000000, v17
	v_fmamk_f32 v23, v30, 0xbc000000, v23
	v_fmamk_f32 v22, v30, 0xbc000000, v22
	v_fmac_f32_e32 v20, 0xbc000000, v30
	v_fmamk_f32 v51, v30, 0xbc000000, v19
	v_fmamk_f32 v50, v30, 0xbc000000, v18
	v_fmac_f32_e32 v16, 0xbc000000, v30
	v_mov_b32_e32 v30, v21
	v_mov_b32_e32 v31, v17
	v_mov_b32_e32 v18, v20
	v_mov_b32_e32 v19, v16
	v_pk_mul_f32 v[30:31], v[30:31], v[30:31]
	v_mov_b32_e32 v34, v23
	v_mov_b32_e32 v35, v51
	v_pk_fma_f32 v[18:19], v[18:19], v[18:19], v[30:31]
	v_mov_b32_e32 v30, v22
	v_mov_b32_e32 v31, v50
	v_pk_mul_f32 v[34:35], v[34:35], v[34:35]
	s_nop 0
	v_pk_fma_f32 v[30:31], v[30:31], v[30:31], v[34:35]
	v_mul_f32_e32 v34, 0xbfb8aa3b, v53
	v_exp_f32_e32 v34, v34
	v_pk_add_f32 v[18:19], v[18:19], v[30:31]
	v_add_f32_e32 v30, 1.0, v32
	v_rcp_f32_e32 v54, v30
	v_add_f32_e32 v30, 1.0, v34
	v_rcp_f32_e32 v55, v30
	ds_read_b128 v[30:33], v91
	ds_read_b128 v[34:37], v91 offset:256
	v_pk_mul_f32 v[52:53], v[54:55], v[52:53]
	s_waitcnt lgkmcnt(1)
	v_mov_b32_e32 v58, v30
	s_waitcnt lgkmcnt(0)
	v_mov_b32_e32 v59, v34
	v_mov_b32_e32 v60, v31
	v_mov_b32_e32 v61, v35
	v_pk_add_f32 v[58:59], v[58:59], v[60:61]
	v_mov_b32_e32 v60, v32
	v_mov_b32_e32 v61, v36
	v_mov_b32_e32 v62, v33
	v_mov_b32_e32 v63, v37
	v_pk_add_f32 v[60:61], v[60:61], v[62:63]
	s_nop 0
	v_pk_add_f32 v[58:59], v[58:59], v[60:61]
	s_nop 0
	v_add_f32_e32 v60, v58, v59
	ds_bpermute_b32 v61, v81, v60
	v_rcp_f32_e32 v58, v40
	v_add_f32_e32 v40, 1.0, v49
	v_rcp_f32_e32 v59, v40
	s_waitcnt lgkmcnt(0)
	v_add_f32_e32 v40, v60, v61
	ds_bpermute_b32 v49, v82, v40
	s_nop 0
	v_lshlrev_b32_e32 v60, 16, v38
	v_mul_f32_e32 v61, 0xbfb8aa3b, v60
	v_exp_f32_e32 v62, v61
	v_and_b32_e32 v61, 0xffff0000, v38
	s_waitcnt lgkmcnt(0)
	v_add_f32_e32 v38, v40, v49
	ds_bpermute_b32 v40, v83, v38
	v_add_f32_e32 v49, 1.0, v62
	v_mul_f32_e32 v62, 0xbfb8aa3b, v61
	v_exp_f32_e32 v63, v62
	v_rcp_f32_e32 v62, v49
	s_waitcnt lgkmcnt(0)
	v_add_f32_e32 v40, v38, v40
	ds_bpermute_b32 v49, v84, v40
	v_add_f32_e32 v38, 1.0, v63
	v_rcp_f32_e32 v63, v38
	v_pk_mul_f32 v[54:55], v[58:59], v[56:57]
	v_lshlrev_b32_e32 v38, 16, v39
	s_waitcnt lgkmcnt(0)
	v_add_f32_e32 v40, v40, v49
	v_fmamk_f32 v31, v40, 0xbc000000, v31
	v_fmamk_f32 v35, v40, 0xbc000000, v35
	v_fmamk_f32 v33, v40, 0xbc000000, v33
	v_fmac_f32_e32 v30, 0xbc000000, v40
	v_fmamk_f32 v37, v40, 0xbc000000, v37
	v_fmac_f32_e32 v34, 0xbc000000, v40
	v_mov_b32_e32 v66, v31
	v_mov_b32_e32 v67, v35
	v_fmamk_f32 v32, v40, 0xbc000000, v32
	v_fmamk_f32 v36, v40, 0xbc000000, v36
	v_mov_b32_e32 v64, v30
	v_mov_b32_e32 v65, v34
	v_pk_mul_f32 v[66:67], v[66:67], v[66:67]
	v_mov_b32_e32 v92, v33
	v_mov_b32_e32 v93, v37
	v_pk_fma_f32 v[64:65], v[64:65], v[64:65], v[66:67]
	v_mov_b32_e32 v66, v32
	v_mov_b32_e32 v67, v36
	v_pk_mul_f32 v[92:93], v[92:93], v[92:93]
	v_pk_mul_f32 v[56:57], v[62:63], v[60:61]
	v_pk_fma_f32 v[66:67], v[66:67], v[66:67], v[92:93]
	v_and_b32_e32 v39, 0xffff0000, v39
	v_pk_add_f32 v[64:65], v[64:65], v[66:67]
	v_mov_b32_e32 v67, v18
	v_mov_b32_e32 v66, v64
	v_mov_b32_e32 v18, v65
	v_pk_add_f32 v[18:19], v[66:67], v[18:19]
	ds_bpermute_b32 v65, v81, v19
	ds_bpermute_b32 v64, v81, v18
	v_mul_f32_e32 v40, 0xbfb8aa3b, v38
	v_exp_f32_e32 v40, v40
	v_mul_f32_e32 v49, 0xbfb8aa3b, v39
	v_exp_f32_e32 v49, v49
	s_waitcnt lgkmcnt(0)
	v_pk_add_f32 v[18:19], v[18:19], v[64:65]
	ds_bpermute_b32 v65, v82, v19
	ds_bpermute_b32 v64, v82, v18
	v_add_f32_e32 v40, 1.0, v40
	v_rcp_f32_e32 v66, v40
	v_add_f32_e32 v40, 1.0, v49
	v_rcp_f32_e32 v67, v40
	s_waitcnt lgkmcnt(0)
	v_pk_add_f32 v[18:19], v[18:19], v[64:65]
	ds_bpermute_b32 v65, v83, v19
	ds_bpermute_b32 v64, v83, v18
	v_pk_mul_f32 v[38:39], v[66:67], v[38:39]
	s_waitcnt lgkmcnt(0)
	v_pk_add_f32 v[58:59], v[18:19], v[64:65]
	ds_bpermute_b32 v61, v84, v59
	ds_bpermute_b32 v60, v84, v58
	v_lshlrev_b64 v[18:19], 12, v[28:29]
	v_lshl_add_u64 v[18:19], s[26:27], 0, v[18:19]
	v_lshl_add_u64 v[28:29], v[18:19], 0, v[46:47]
	v_add_u32_e32 v18, s36, v90
	s_waitcnt lgkmcnt(0)
; DI float siluf_(float x) { return x * frcp(1.f + fexp(-x)); }
; DI u32x2 pack4(const f32x4 a) { u32x2 w; w.x = pk2(a[0], a[1]); w.y = pk2(a[2], a[3]); return w; }
; DI void conv_item(LAS unsigned char* lds, int item, const bf16_t* P, const float* cw, const float* cb, const float* lng, const float* lnb, bf16_t* MIX) {
;     ...
;             const float rstd = rsqrtf(sq * (1.f / 128.f) + EPS_);
;             f32x4 oa = va * rstd * ga + ba, ob = vb * rstd * gb + bb;
;             oa[0] = siluf_(oa[0]) * siluf_(bflo(za.x)); oa[1] = siluf_(oa[1]) * siluf_(bfhi(za.x)); oa[2] = siluf_(oa[2]) * siluf_(bflo(za.y)); oa[3] = siluf_(oa[3]) * siluf_(bfhi(za.y));
;             ob[0] = siluf_(ob[0]) * siluf_(bflo(zb.x)); ob[1] = siluf_(ob[1]) * siluf_(bfhi(zb.x)); ob[2] = siluf_(ob[2]) * siluf_(bflo(zb.y)); ob[3] = siluf_(ob[3]) * siluf_(bfhi(zb.y));
;             *(u32x2*)(MIX + row * DM + cbase + ca) = pack4(oa); *(u32x2*)(MIX + row * DM + cbase + cb2) = pack4(ob);
;         }
;     }
	v_pk_add_f32 v[58:59], v[58:59], v[60:61]
	v_mad_i64_i32 v[24:25], s[36:37], v18, s30, v[24:25]
	v_pk_fma_f32 v[26:27], v[58:59], s[20:21], v[26:27] op_sel_hi:[1,0,0]
	v_lshl_add_u64 v[24:25], v[24:25], 0, s[12:13]
	v_mul_f32_e32 v19, 0x4b800000, v27
	v_cmp_gt_f32_e32 vcc, s34, v27
	v_lshl_add_u64 v[24:25], v[24:25], 0, v[46:47]
	s_add_i32 s21, s21, s23
	v_cndmask_b32_e32 v19, v27, v19, vcc
	v_rsq_f32_e32 v19, v19
	s_cmpk_gt_i32 s35, 0x1ff
	v_mul_f32_e32 v27, 0x45800000, v19
	v_cndmask_b32_e32 v40, v19, v27, vcc
	v_pk_mul_f32 v[20:21], v[20:21], v[40:41] op_sel_hi:[1,0]
	v_pk_mul_f32 v[22:23], v[22:23], v[40:41] op_sel_hi:[1,0]
	v_pk_fma_f32 v[20:21], v[8:9], v[20:21], v[12:13]
	v_pk_fma_f32 v[22:23], v[10:11], v[22:23], v[14:15]
	v_mul_f32_e32 v19, 0xbfb8aa3b, v20
	v_exp_f32_e32 v19, v19
	v_mul_f32_e32 v27, 0xbfb8aa3b, v21
	v_exp_f32_e32 v27, v27
	v_pk_mul_f32 v[16:17], v[16:17], v[40:41] op_sel_hi:[1,0]
	v_add_f32_e32 v19, 1.0, v19
	v_rcp_f32_e32 v58, v19
	v_add_f32_e32 v19, 1.0, v27
	v_rcp_f32_e32 v59, v19
	v_mul_f32_e32 v19, 0xbfb8aa3b, v22
	v_exp_f32_e32 v19, v19
	v_mul_f32_e32 v27, 0xbfb8aa3b, v23
	v_exp_f32_e32 v27, v27
	v_pk_mul_f32 v[20:21], v[20:21], v[58:59]
	v_add_f32_e32 v19, 1.0, v19
	v_pk_fma_f32 v[16:17], v[0:1], v[16:17], v[4:5]
	v_pk_mul_f32 v[20:21], v[52:53], v[20:21]
	v_rcp_f32_e32 v52, v19
	v_add_f32_e32 v19, 1.0, v27
	v_rcp_f32_e32 v53, v19
	v_mul_f32_e32 v19, 0xbfb8aa3b, v16
	v_exp_f32_e32 v19, v19
	v_mul_f32_e32 v27, 0xbfb8aa3b, v17
	v_exp_f32_e32 v27, v27
	v_pk_mul_f32 v[50:51], v[50:51], v[40:41] op_sel_hi:[1,0]
	v_add_f32_e32 v19, 1.0, v19
	v_pk_fma_f32 v[50:51], v[2:3], v[50:51], v[6:7]
	v_pk_mul_f32 v[22:23], v[22:23], v[52:53]
	v_rcp_f32_e32 v52, v19
	v_add_f32_e32 v19, 1.0, v27
	v_mul_f32_e32 v27, 0xbfb8aa3b, v50
	v_exp_f32_e32 v27, v27
	v_mul_f32_e32 v40, 0xbfb8aa3b, v51
	v_exp_f32_e32 v40, v40
	v_rcp_f32_e32 v53, v19
	v_add_f32_e32 v19, 1.0, v27
	v_rcp_f32_e32 v58, v19
	v_add_f32_e32 v19, 1.0, v40
	v_rcp_f32_e32 v59, v19
	v_pk_mul_f32 v[16:17], v[16:17], v[52:53]
	v_pk_mul_f32 v[22:23], v[54:55], v[22:23]
	v_pk_mul_f32 v[16:17], v[56:57], v[16:17]
	v_pk_mul_f32 v[50:51], v[50:51], v[58:59]
	v_cvt_pk_bf16_f32 v16, v16, v17
	v_pk_mul_f32 v[38:39], v[38:39], v[50:51]
	v_cvt_pk_bf16_f32 v20, v20, v21
	v_cvt_pk_bf16_f32 v17, v38, v39
	v_cvt_pk_bf16_f32 v21, v22, v23
	global_store_dwordx2 v[28:29], v[16:17], off offset:128
	v_add_co_u32_e32 v16, vcc, s31, v24
	global_store_dwordx2 v[28:29], v[20:21], off
	s_nop 0
	v_addc_co_u32_e32 v17, vcc, 0, v25, vcc
	v_mov_b32_e32 v16, v138
	v_mov_b32_e32 v17, v139
	v_lshl_add_u64 v[20:21], v[24:25], 0, s[18:19]
	v_mov_b32_e32 v20, v140
	v_mov_b32_e32 v21, v141
	v_mul_f32_e32 v19, 0x4b800000, v26
	v_cmp_gt_f32_e32 vcc, s34, v26
	s_nop 1
	v_cndmask_b32_e32 v19, v26, v19, vcc
	v_rsq_f32_e32 v22, v19
	v_ashrrev_i32_e32 v19, 31, v18
	v_mul_f32_e32 v23, 0x45800000, v22
	v_cndmask_b32_e32 v22, v22, v23, vcc
	v_pk_mul_f32 v[24:25], v[30:31], v[22:23] op_sel_hi:[1,0]
	v_pk_mul_f32 v[26:27], v[32:33], v[22:23] op_sel_hi:[1,0]
	v_pk_fma_f32 v[8:9], v[8:9], v[24:25], v[12:13]
	v_pk_fma_f32 v[10:11], v[10:11], v[26:27], v[14:15]
	v_pk_mul_f32 v[14:15], v[36:37], v[22:23] op_sel_hi:[1,0]
	v_pk_mul_f32 v[12:13], v[34:35], v[22:23] op_sel_hi:[1,0]
	v_pk_fma_f32 v[2:3], v[2:3], v[14:15], v[6:7]
	v_mul_f32_e32 v6, 0xbfb8aa3b, v8
	v_exp_f32_e32 v6, v6
	v_mul_f32_e32 v7, 0xbfb8aa3b, v9
	v_exp_f32_e32 v7, v7
	v_pk_fma_f32 v[0:1], v[0:1], v[12:13], v[4:5]
	v_add_f32_e32 v4, 1.0, v6
	v_rcp_f32_e32 v4, v4
	v_add_f32_e32 v5, 1.0, v7
	v_rcp_f32_e32 v5, v5
	s_nop 0
	v_lshlrev_b32_e32 v6, 16, v16
	v_mul_f32_e32 v7, 0xbfb8aa3b, v6
	v_exp_f32_e32 v12, v7
	v_and_b32_e32 v7, 0xffff0000, v16
	v_mul_f32_e32 v13, 0xbfb8aa3b, v7
	v_exp_f32_e32 v13, v13
	v_pk_mul_f32 v[4:5], v[8:9], v[4:5]
	v_mul_f32_e32 v9, 0xbfb8aa3b, v10
	v_exp_f32_e32 v9, v9
	v_add_f32_e32 v8, 1.0, v13
	v_mul_f32_e32 v13, 0xbfb8aa3b, v11
	v_exp_f32_e32 v14, v13
	v_rcp_f32_e32 v13, v8
	v_add_f32_e32 v8, 1.0, v9
	v_and_b32_e32 v15, 0xffff0000, v17
	v_add_f32_e32 v9, 1.0, v14
	v_lshlrev_b32_e32 v14, 16, v17
	v_add_f32_e32 v12, 1.0, v12
	v_mul_f32_e32 v16, 0xbfb8aa3b, v14
	v_mul_f32_e32 v17, 0xbfb8aa3b, v15
	v_rcp_f32_e32 v12, v12
	v_exp_f32_e32 v16, v16
	v_exp_f32_e32 v17, v17
	v_rcp_f32_e32 v8, v8
	v_rcp_f32_e32 v9, v9
	v_add_f32_e32 v16, 1.0, v16
	v_add_f32_e32 v17, 1.0, v17
	v_pk_mul_f32 v[6:7], v[12:13], v[6:7]
	v_rcp_f32_e32 v16, v16
	v_rcp_f32_e32 v17, v17
	v_pk_mul_f32 v[4:5], v[6:7], v[4:5]
	v_pk_mul_f32 v[6:7], v[10:11], v[8:9]
	v_mul_f32_e32 v10, 0xbfb8aa3b, v0
	v_exp_f32_e32 v10, v10
	v_mul_f32_e32 v11, 0xbfb8aa3b, v1
	v_exp_f32_e32 v11, v11
	v_pk_mul_f32 v[8:9], v[16:17], v[14:15]
	s_nop 0
	v_and_b32_e32 v15, 0xffff0000, v21
	v_pk_mul_f32 v[6:7], v[8:9], v[6:7]
	v_add_f32_e32 v8, 1.0, v10
	v_lshlrev_b32_e32 v10, 16, v20
	v_add_f32_e32 v9, 1.0, v11
	v_mul_f32_e32 v11, 0xbfb8aa3b, v10
	v_exp_f32_e32 v12, v11
	v_and_b32_e32 v11, 0xffff0000, v20
	v_mul_f32_e32 v13, 0xbfb8aa3b, v11
	v_rcp_f32_e32 v8, v8
	v_rcp_f32_e32 v9, v9
	v_exp_f32_e32 v13, v13
	v_mul_f32_e32 v17, 0xbfb8aa3b, v15
	v_exp_f32_e32 v17, v17
	v_pk_mul_f32 v[0:1], v[0:1], v[8:9]
	v_add_f32_e32 v8, 1.0, v13
	v_mul_f32_e32 v9, 0xbfb8aa3b, v2
	v_mul_f32_e32 v13, 0xbfb8aa3b, v3
	v_exp_f32_e32 v9, v9
	v_exp_f32_e32 v14, v13
	v_rcp_f32_e32 v13, v8
	v_add_f32_e32 v12, 1.0, v12
	v_add_f32_e32 v8, 1.0, v9
	v_add_f32_e32 v9, 1.0, v14
	v_lshlrev_b32_e32 v14, 16, v21
	v_mul_f32_e32 v16, 0xbfb8aa3b, v14
	v_exp_f32_e32 v16, v16
	v_add_f32_e32 v17, 1.0, v17
	v_rcp_f32_e32 v12, v12
	v_rcp_f32_e32 v8, v8
	v_add_f32_e32 v16, 1.0, v16
	v_rcp_f32_e32 v9, v9
	v_rcp_f32_e32 v16, v16
	v_rcp_f32_e32 v17, v17
	v_pk_mul_f32 v[10:11], v[12:13], v[10:11]
	v_pk_mul_f32 v[2:3], v[2:3], v[8:9]
	v_cvt_pk_bf16_f32 v4, v4, v5
	v_pk_mul_f32 v[8:9], v[16:17], v[14:15]
	v_cvt_pk_bf16_f32 v5, v6, v7
	v_lshlrev_b64 v[6:7], 12, v[18:19]
	v_pk_mul_f32 v[0:1], v[10:11], v[0:1]
	v_pk_mul_f32 v[2:3], v[8:9], v[2:3]
	v_lshl_add_u64 v[6:7], s[26:27], 0, v[6:7]
	v_lshl_add_u64 v[6:7], v[6:7], 0, v[46:47]
	v_cvt_pk_bf16_f32 v0, v0, v1
	v_cvt_pk_bf16_f32 v1, v2, v3
	global_store_dwordx2 v[6:7], v[4:5], off
	global_store_dwordx2 v[6:7], v[0:1], off offset:128
	s_barrier
	s_cbranch_scc1 .LBB0_532
